# hand-written E_PROJ epilogues (all gate / running-sum loads ahead of the stores) on top of the cvt rewrites
# speedup vs baseline: 1.0057x; 1.0057x over previous
; #define PG8_STAGE(bufoff, gbase, voff) do { _Pragma("unroll") for (int _i = 0; _i < 2; ++_i) \
;     __builtin_amdgcn_global_load_lds((const unsigned*)((const char*)(gbase) + (voff)[_i]), (LAS unsigned*)(lds + (bufoff) + ldsw + _i * 8192), 16, 0, 0); } while (0)
; #define PG8_LDA(dst, b, h) do { _Pragma("unroll") for (int m = 0; m < 4; ++m) _Pragma("unroll") for (int k = 0; k < 2; ++k) dst[m][k] = *(const LAS bf16x8*)(lds + PG8_SA(b, h) + aoff + m * 2048 + k * 1024); } while (0)
; #define PG8_LDB(dst, b, h) do { _Pragma("unroll") for (int n = 0; n < 2; ++n) _Pragma("unroll") for (int k = 0; k < 2; ++k) dst[n][k] = *(const LAS bf16x8*)(lds + PG8_SB(b, h) + boff + n * 2048 + k * 1024); } while (0)
; #define PG8_MMA(ai, bj, At, Bt) do { __builtin_amdgcn_s_setprio(1); _Pragma("unroll") for (int m = 0; m < 4; ++m) _Pragma("unroll") for (int n = 0; n < 2; ++n) _Pragma("unroll") for (int k = 0; k < 2; ++k) \
;     acc[ai][bj][m][n] = __builtin_amdgcn_mfma_f32_16x16x32_bf16(Bt[n][k], At[m][k], acc[ai][bj][m][n], 0, 0, 0); __builtin_amdgcn_s_setprio(0); } while (0)
; #define PG8_WAIT_L(n) asm volatile("s_waitcnt lgkmcnt(" #n ")" ::: "memory")
; #define PG8_BAR __builtin_amdgcn_s_barrier()
; #define PG8_SCHED __builtin_amdgcn_sched_barrier(0)
; template <class Epi>
; __device__ __forceinline__ void gemm_phase(LAS unsigned char* lds, const Gemm g, const StaticOrder& S, const Epi& E, int wv0) {
;     ...
;       PG8_LDB(B0, 0, 0); PG8_SCHED; PG8_LDA(At, 0, 0); PG8_STAGE(PG8_SA(1, 1), a1 + hstepA, voffA);
;       PG8_WAIT_L(8); PG8_BAR; PG8_WAIT_L(0); PG8_MMA(0, 0, At, B0); PG8_BAR; PG8_SCHED;
;       PG8_LDB(B1, 0, 1); PG8_STAGE(PG8_SB(0, 0), b2, voffB);
;       PG8_BAR; PG8_WAIT_L(0); PG8_MMA(0, 1, At, B1); PG8_BAR;
;       PG8_LDA(At, 0, 1); PG8_STAGE(PG8_SA(0, 0), a2, voffA);
;       PG8_BAR; PG8_WAIT_L(0); PG8_MMA(1, 0, At, B0); PG8_BAR; PG8_SCHED;
;       PG8_STAGE(PG8_SB(0, 1), b2 + hstepB, voffB);
.LBB0_981:
	s_add_u32 s4, s18, 0x100
	s_addc_u32 s5, s19, 0
	s_add_i32 s0, 0, 0x10000
	v_add_u32_e32 v142, s0, v173
	ds_read_b128 v[130:133], v142
	ds_read_b128 v[134:137], v142 offset:1024
	ds_read_b128 v[138:141], v142 offset:2048
	ds_read_b128 v[142:145], v142 offset:3072
	s_cmp_eq_u32 s49, 12
	s_cselect_b32 s23, s15, s5
	s_cselect_b32 s22, s14, s4
	s_cselect_b32 s21, s13, s48
	s_cselect_b32 s20, s46, s47
	v_lshl_add_u64 v[192:193], s[18:19], 0, v[156:157]
	s_add_i32 m0, s36, 0xc000
	ds_read_b128 v[146:149], v175
	ds_read_b128 v[160:163], v175 offset:1024
	ds_read_b128 v[164:167], v175 offset:2048
	ds_read_b128 v[168:171], v175 offset:3072
	ds_read_b128 v[176:179], v175 offset:4096
	ds_read_b128 v[180:183], v175 offset:5120
	ds_read_b128 v[184:187], v175 offset:6144
	ds_read_b128 v[188:191], v175 offset:7168
	global_load_lds_dwordx4 v[192:193], off
	v_lshl_add_u64 v[192:193], s[18:19], 0, v[158:159]
	s_add_i32 m0, s36, 0xe000
	s_nop 0
	global_load_lds_dwordx4 v[192:193], off
	s_waitcnt lgkmcnt(8)
	s_barrier
	s_waitcnt lgkmcnt(0)
	s_setprio 1
	s_waitcnt lgkmcnt(0)
	v_mfma_f32_16x16x32_bf16 v[126:129], v[130:133], v[146:149], v[126:129]
	v_mfma_f32_16x16x32_bf16 v[122:125], v[138:141], v[146:149], v[122:125]
	v_mfma_f32_16x16x32_bf16 v[118:121], v[130:133], v[164:167], v[118:121]
	v_mfma_f32_16x16x32_bf16 v[110:113], v[138:141], v[164:167], v[110:113]
	v_mfma_f32_16x16x32_bf16 v[92:95], v[130:133], v[176:179], v[92:95]
	v_mfma_f32_16x16x32_bf16 v[88:91], v[138:141], v[176:179], v[88:91]
	v_mfma_f32_16x16x32_bf16 v[80:83], v[130:133], v[184:187], v[80:83]
	v_mfma_f32_16x16x32_bf16 v[72:75], v[138:141], v[184:187], v[72:75]
	v_mfma_f32_16x16x32_bf16 v[126:129], v[134:137], v[160:163], v[126:129]
	v_mfma_f32_16x16x32_bf16 v[122:125], v[142:145], v[160:163], v[122:125]
	v_mfma_f32_16x16x32_bf16 v[118:121], v[134:137], v[168:171], v[118:121]
	v_mfma_f32_16x16x32_bf16 v[110:113], v[142:145], v[168:171], v[110:113]
	v_mfma_f32_16x16x32_bf16 v[92:95], v[134:137], v[180:183], v[92:95]
	v_mfma_f32_16x16x32_bf16 v[88:91], v[142:145], v[180:183], v[88:91]
	v_mfma_f32_16x16x32_bf16 v[80:83], v[134:137], v[188:191], v[80:83]
	v_mfma_f32_16x16x32_bf16 v[72:75], v[142:145], v[188:191], v[72:75]
	s_setprio 0
	s_barrier
	s_add_i32 s50, 0, 0x14000
	s_add_i32 s0, s0, s35
	v_add_u32_e32 v204, s50, v173
	v_lshl_add_u64 v[208:209], s[20:21], 0, v[96:97]
	s_mov_b32 m0, s0
	ds_read_b128 v[192:195], v204
	ds_read_b128 v[196:199], v204 offset:1024
	ds_read_b128 v[200:203], v204 offset:2048
	ds_read_b128 v[204:207], v204 offset:3072
	global_load_lds_dwordx4 v[208:209], off
	v_lshl_add_u64 v[210:211], s[20:21], 0, v[154:155]
	s_add_i32 m0, s0, 0x2000
	s_nop 0
	global_load_lds_dwordx4 v[210:211], off
	s_barrier
	s_waitcnt lgkmcnt(0)
	s_setprio 1
	s_waitcnt lgkmcnt(0)
	v_mfma_f32_16x16x32_bf16 v[114:117], v[192:195], v[146:149], v[114:117]
	v_mfma_f32_16x16x32_bf16 v[106:109], v[200:203], v[146:149], v[106:109]
	v_mfma_f32_16x16x32_bf16 v[102:105], v[192:195], v[164:167], v[102:105]
	v_mfma_f32_16x16x32_bf16 v[98:101], v[200:203], v[164:167], v[98:101]
	v_mfma_f32_16x16x32_bf16 v[84:87], v[192:195], v[176:179], v[84:87]
	v_mfma_f32_16x16x32_bf16 v[76:79], v[200:203], v[176:179], v[76:79]
	v_mfma_f32_16x16x32_bf16 v[68:71], v[192:195], v[184:187], v[68:71]
	v_mfma_f32_16x16x32_bf16 v[64:67], v[200:203], v[184:187], v[64:67]
	v_mfma_f32_16x16x32_bf16 v[114:117], v[196:199], v[160:163], v[114:117]
	v_mfma_f32_16x16x32_bf16 v[106:109], v[204:207], v[160:163], v[106:109]
	v_mfma_f32_16x16x32_bf16 v[102:105], v[196:199], v[168:171], v[102:105]
	v_mfma_f32_16x16x32_bf16 v[98:101], v[204:207], v[168:171], v[98:101]
	v_mfma_f32_16x16x32_bf16 v[84:87], v[196:199], v[180:183], v[84:87]
	v_mfma_f32_16x16x32_bf16 v[76:79], v[204:207], v[180:183], v[76:79]
	v_mfma_f32_16x16x32_bf16 v[68:71], v[196:199], v[188:191], v[68:71]
	v_mfma_f32_16x16x32_bf16 v[64:67], v[204:207], v[188:191], v[64:67]
	s_setprio 0
	s_mov_b32 m0, s36
	v_lshl_add_u64 v[212:213], s[22:23], 0, v[150:151]
	s_barrier
	ds_read_b128 v[146:149], v175 offset:16384
	ds_read_b128 v[160:163], v175 offset:17408
	ds_read_b128 v[164:167], v175 offset:18432
	ds_read_b128 v[168:171], v175 offset:19456
	ds_read_b128 v[176:179], v175 offset:20480
	ds_read_b128 v[180:183], v175 offset:21504
	ds_read_b128 v[184:187], v175 offset:22528
	ds_read_b128 v[188:191], v175 offset:23552
	global_load_lds_dwordx4 v[212:213], off
	v_lshl_add_u64 v[214:215], s[22:23], 0, v[152:153]
	s_mov_b32 m0, s37
	s_nop 0
	global_load_lds_dwordx4 v[214:215], off
	s_barrier
	s_waitcnt lgkmcnt(0)
	s_setprio 1
	s_waitcnt lgkmcnt(0)
	v_mfma_f32_16x16x32_bf16 v[60:63], v[130:133], v[146:149], v[60:63]
	v_mfma_f32_16x16x32_bf16 v[56:59], v[138:141], v[146:149], v[56:59]
	v_mfma_f32_16x16x32_bf16 v[48:51], v[130:133], v[164:167], v[48:51]
	v_mfma_f32_16x16x32_bf16 v[40:43], v[138:141], v[164:167], v[40:43]
	v_mfma_f32_16x16x32_bf16 v[32:35], v[130:133], v[176:179], v[32:35]
	v_mfma_f32_16x16x32_bf16 v[24:27], v[138:141], v[176:179], v[24:27]
	v_mfma_f32_16x16x32_bf16 v[16:19], v[130:133], v[184:187], v[16:19]
	v_mfma_f32_16x16x32_bf16 v[8:11], v[138:141], v[184:187], v[8:11]
	v_mfma_f32_16x16x32_bf16 v[60:63], v[134:137], v[160:163], v[60:63]
	v_mfma_f32_16x16x32_bf16 v[56:59], v[142:145], v[160:163], v[56:59]
	v_mfma_f32_16x16x32_bf16 v[48:51], v[134:137], v[168:171], v[48:51]
	v_mfma_f32_16x16x32_bf16 v[40:43], v[142:145], v[168:171], v[40:43]
	v_mfma_f32_16x16x32_bf16 v[32:35], v[134:137], v[180:183], v[32:35]
	v_mfma_f32_16x16x32_bf16 v[24:27], v[142:145], v[180:183], v[24:27]
	v_mfma_f32_16x16x32_bf16 v[16:19], v[134:137], v[188:191], v[16:19]
	v_mfma_f32_16x16x32_bf16 v[8:11], v[142:145], v[188:191], v[8:11]
	s_setprio 0
	s_barrier
; #define PG8_STAGE(bufoff, gbase, voff) do { _Pragma("unroll") for (int _i = 0; _i < 2; ++_i) \
;     __builtin_amdgcn_global_load_lds((const unsigned*)((const char*)(gbase) + (voff)[_i]), (LAS unsigned*)(lds + (bufoff) + ldsw + _i * 8192), 16, 0, 0); } while (0)
; #define PG8_LDA(dst, b, h) do { _Pragma("unroll") for (int m = 0; m < 4; ++m) _Pragma("unroll") for (int k = 0; k < 2; ++k) dst[m][k] = *(const LAS bf16x8*)(lds + PG8_SA(b, h) + aoff + m * 2048 + k * 1024); } while (0)
; #define PG8_LDB(dst, b, h) do { _Pragma("unroll") for (int n = 0; n < 2; ++n) _Pragma("unroll") for (int k = 0; k < 2; ++k) dst[n][k] = *(const LAS bf16x8*)(lds + PG8_SB(b, h) + boff + n * 2048 + k * 1024); } while (0)
; #define PG8_MMA(ai, bj, At, Bt) do { __builtin_amdgcn_s_setprio(1); _Pragma("unroll") for (int m = 0; m < 4; ++m) _Pragma("unroll") for (int n = 0; n < 2; ++n) _Pragma("unroll") for (int k = 0; k < 2; ++k) \
;     acc[ai][bj][m][n] = __builtin_amdgcn_mfma_f32_16x16x32_bf16(Bt[n][k], At[m][k], acc[ai][bj][m][n], 0, 0, 0); __builtin_amdgcn_s_setprio(0); } while (0)
; #define PG8_WAIT_V(n) asm volatile("s_waitcnt vmcnt(" #n ")" ::: "memory")
; #define PG8_WAIT_L(n) asm volatile("s_waitcnt lgkmcnt(" #n ")" ::: "memory")
; #define PG8_BAR __builtin_amdgcn_s_barrier()
; #define PG8_SCHED __builtin_amdgcn_sched_barrier(0)
; template <class Epi>
; __device__ __forceinline__ void gemm_phase(LAS unsigned char* lds, const Gemm g, const StaticOrder& S, const Epi& E, int wv0) {
;     ...
;       PG8_STAGE(PG8_SB(0, 1), b2 + hstepB, voffB);
;       PG8_WAIT_V(6); PG8_BAR; PG8_MMA(1, 1, At, B1); PG8_BAR;
;       PG8_LDB(B0, 1, 0); PG8_SCHED; PG8_LDA(At, 1, 0); PG8_STAGE(PG8_SA(0, 1), a2 + hstepA, voffA);
;       PG8_WAIT_L(8); PG8_BAR; PG8_WAIT_L(0); PG8_MMA(0, 0, At, B0); PG8_BAR; PG8_SCHED;
;       PG8_LDB(B1, 1, 1); PG8_STAGE(PG8_SB(1, 0), b3, voffB);
;       PG8_BAR; PG8_WAIT_L(0); PG8_MMA(0, 1, At, B1); PG8_BAR;
;       PG8_LDA(At, 1, 1); PG8_STAGE(PG8_SA(1, 0), a3, voffA);
	s_add_u32 s18, s20, 0x40000
	s_addc_u32 s19, s21, 0
	s_add_i32 s0, s50, s35
	v_lshl_add_u64 v[130:131], s[18:19], 0, v[96:97]
	s_mov_b32 m0, s0
	s_nop 0
	global_load_lds_dwordx4 v[130:131], off
	v_lshl_add_u64 v[130:131], s[18:19], 0, v[154:155]
	s_add_i32 m0, s0, 0x2000
	s_nop 0
	global_load_lds_dwordx4 v[130:131], off
	s_waitcnt vmcnt(6)
	s_barrier
	s_setprio 1
	v_mfma_f32_16x16x32_bf16 v[52:55], v[192:195], v[146:149], v[52:55]
	v_mfma_f32_16x16x32_bf16 v[44:47], v[200:203], v[146:149], v[44:47]
	v_mfma_f32_16x16x32_bf16 v[36:39], v[192:195], v[164:167], v[36:39]
	v_mfma_f32_16x16x32_bf16 v[28:31], v[200:203], v[164:167], v[28:31]
	v_mfma_f32_16x16x32_bf16 v[20:23], v[192:195], v[176:179], v[20:23]
	v_mfma_f32_16x16x32_bf16 v[12:15], v[200:203], v[176:179], v[12:15]
	v_mfma_f32_16x16x32_bf16 v[4:7], v[192:195], v[184:187], v[4:7]
	v_mfma_f32_16x16x32_bf16 v[0:3], v[200:203], v[184:187], v[0:3]
	v_mfma_f32_16x16x32_bf16 v[52:55], v[196:199], v[160:163], v[52:55]
	v_mfma_f32_16x16x32_bf16 v[44:47], v[204:207], v[160:163], v[44:47]
	v_mfma_f32_16x16x32_bf16 v[36:39], v[196:199], v[168:171], v[36:39]
	v_mfma_f32_16x16x32_bf16 v[28:31], v[204:207], v[168:171], v[28:31]
	v_mfma_f32_16x16x32_bf16 v[20:23], v[196:199], v[180:183], v[20:23]
	v_mfma_f32_16x16x32_bf16 v[12:15], v[204:207], v[180:183], v[12:15]
	v_mfma_f32_16x16x32_bf16 v[4:7], v[196:199], v[188:191], v[4:7]
	v_mfma_f32_16x16x32_bf16 v[0:3], v[204:207], v[188:191], v[0:3]
	s_setprio 0
	s_add_i32 s0, 0, 0x18000
	v_add_u32_e32 v142, s0, v173
	s_barrier
	ds_read_b128 v[130:133], v142
	ds_read_b128 v[134:137], v142 offset:1024
	ds_read_b128 v[138:141], v142 offset:2048
	ds_read_b128 v[142:145], v142 offset:3072
	s_add_u32 s18, s22, 0x114000
	s_addc_u32 s19, s23, 0
	s_mov_b32 m0, s38
	v_lshl_add_u64 v[192:193], s[18:19], 0, v[150:151]
	ds_read_b128 v[146:149], v175 offset:32768
	ds_read_b128 v[160:163], v175 offset:33792
	ds_read_b128 v[164:167], v175 offset:34816
	ds_read_b128 v[168:171], v175 offset:35840
	ds_read_b128 v[176:179], v175 offset:36864
	ds_read_b128 v[180:183], v175 offset:37888
	ds_read_b128 v[184:187], v175 offset:38912
	ds_read_b128 v[188:191], v175 offset:39936
	global_load_lds_dwordx4 v[192:193], off
	v_lshl_add_u64 v[192:193], s[18:19], 0, v[152:153]
	s_mov_b32 m0, s39
	s_nop 0
	global_load_lds_dwordx4 v[192:193], off
	s_waitcnt lgkmcnt(8)
	s_barrier
	s_waitcnt lgkmcnt(0)
	s_setprio 1
	s_waitcnt lgkmcnt(0)
	v_mfma_f32_16x16x32_bf16 v[126:129], v[130:133], v[146:149], v[126:129]
	v_mfma_f32_16x16x32_bf16 v[122:125], v[138:141], v[146:149], v[122:125]
	v_mfma_f32_16x16x32_bf16 v[118:121], v[130:133], v[164:167], v[118:121]
	v_mfma_f32_16x16x32_bf16 v[110:113], v[138:141], v[164:167], v[110:113]
	v_mfma_f32_16x16x32_bf16 v[92:95], v[130:133], v[176:179], v[92:95]
	v_mfma_f32_16x16x32_bf16 v[88:91], v[138:141], v[176:179], v[88:91]
	v_mfma_f32_16x16x32_bf16 v[80:83], v[130:133], v[184:187], v[80:83]
	v_mfma_f32_16x16x32_bf16 v[72:75], v[138:141], v[184:187], v[72:75]
	v_mfma_f32_16x16x32_bf16 v[126:129], v[134:137], v[160:163], v[126:129]
	v_mfma_f32_16x16x32_bf16 v[122:125], v[142:145], v[160:163], v[122:125]
	v_mfma_f32_16x16x32_bf16 v[118:121], v[134:137], v[168:171], v[118:121]
	v_mfma_f32_16x16x32_bf16 v[110:113], v[142:145], v[168:171], v[110:113]
	v_mfma_f32_16x16x32_bf16 v[92:95], v[134:137], v[180:183], v[92:95]
	v_mfma_f32_16x16x32_bf16 v[88:91], v[142:145], v[180:183], v[88:91]
	v_mfma_f32_16x16x32_bf16 v[80:83], v[134:137], v[188:191], v[80:83]
	v_mfma_f32_16x16x32_bf16 v[72:75], v[142:145], v[188:191], v[72:75]
	s_setprio 0
	s_barrier
	s_add_i32 s22, 0, 0x1c000
	s_add_i32 s0, s0, s35
	v_add_u32_e32 v204, s22, v173
	v_lshl_add_u64 v[208:209], v[208:209], 0, s[72:73]
	s_mov_b32 m0, s0
	ds_read_b128 v[192:195], v204
	ds_read_b128 v[196:199], v204 offset:1024
	ds_read_b128 v[200:203], v204 offset:2048
	ds_read_b128 v[204:207], v204 offset:3072
	global_load_lds_dwordx4 v[208:209], off
	v_lshl_add_u64 v[208:209], v[210:211], 0, s[72:73]
	s_add_i32 m0, s0, 0x2000
	s_nop 0
	global_load_lds_dwordx4 v[208:209], off
	s_barrier
	s_waitcnt lgkmcnt(0)
	s_setprio 1
	s_waitcnt lgkmcnt(0)
	v_mfma_f32_16x16x32_bf16 v[114:117], v[192:195], v[146:149], v[114:117]
	v_mfma_f32_16x16x32_bf16 v[106:109], v[200:203], v[146:149], v[106:109]
	v_mfma_f32_16x16x32_bf16 v[102:105], v[192:195], v[164:167], v[102:105]
	v_mfma_f32_16x16x32_bf16 v[98:101], v[200:203], v[164:167], v[98:101]
	v_mfma_f32_16x16x32_bf16 v[84:87], v[192:195], v[176:179], v[84:87]
	v_mfma_f32_16x16x32_bf16 v[76:79], v[200:203], v[176:179], v[76:79]
	v_mfma_f32_16x16x32_bf16 v[68:71], v[192:195], v[184:187], v[68:71]
	v_mfma_f32_16x16x32_bf16 v[64:67], v[200:203], v[184:187], v[64:67]
	v_mfma_f32_16x16x32_bf16 v[114:117], v[196:199], v[160:163], v[114:117]
	v_mfma_f32_16x16x32_bf16 v[106:109], v[204:207], v[160:163], v[106:109]
	v_mfma_f32_16x16x32_bf16 v[102:105], v[196:199], v[168:171], v[102:105]
	v_mfma_f32_16x16x32_bf16 v[98:101], v[204:207], v[168:171], v[98:101]
	v_mfma_f32_16x16x32_bf16 v[84:87], v[196:199], v[180:183], v[84:87]
	v_mfma_f32_16x16x32_bf16 v[76:79], v[204:207], v[180:183], v[76:79]
	v_mfma_f32_16x16x32_bf16 v[68:71], v[196:199], v[188:191], v[68:71]
	v_mfma_f32_16x16x32_bf16 v[64:67], v[204:207], v[188:191], v[64:67]
	s_setprio 0
	s_mov_b32 m0, s40
	v_lshl_add_u64 v[208:209], v[212:213], 0, s[72:73]
	s_barrier
	ds_read_b128 v[146:149], v175 offset:49152
	ds_read_b128 v[160:163], v175 offset:50176
	ds_read_b128 v[164:167], v175 offset:51200
	ds_read_b128 v[168:171], v175 offset:52224
	ds_read_b128 v[176:179], v175 offset:53248
	ds_read_b128 v[180:183], v175 offset:54272
	ds_read_b128 v[184:187], v175 offset:55296
	ds_read_b128 v[188:191], v175 offset:56320
	global_load_lds_dwordx4 v[208:209], off
	v_lshl_add_u64 v[208:209], v[214:215], 0, s[72:73]
	s_mov_b32 m0, s41
	s_nop 0
	global_load_lds_dwordx4 v[208:209], off
	s_barrier
; __device__ __forceinline__ float bf_lo(unsigned u) { return __uint_as_float(u << 16); }
; __device__ __forceinline__ float bf_hi(unsigned u) { return __uint_as_float(u & 0xffff0000u); }
; #define PG8_STAGE(bufoff, gbase, voff) do { _Pragma("unroll") for (int _i = 0; _i < 2; ++_i) \
;     __builtin_amdgcn_global_load_lds((const unsigned*)((const char*)(gbase) + (voff)[_i]), (LAS unsigned*)(lds + (bufoff) + ldsw + _i * 8192), 16, 0, 0); } while (0)
; #define PG8_MMA(ai, bj, At, Bt) do { __builtin_amdgcn_s_setprio(1); _Pragma("unroll") for (int m = 0; m < 4; ++m) _Pragma("unroll") for (int n = 0; n < 2; ++n) _Pragma("unroll") for (int k = 0; k < 2; ++k) \
;     acc[ai][bj][m][n] = __builtin_amdgcn_mfma_f32_16x16x32_bf16(Bt[n][k], At[m][k], acc[ai][bj][m][n], 0, 0, 0); __builtin_amdgcn_s_setprio(0); } while (0)
; #define PG8_WAIT_V(n) asm volatile("s_waitcnt vmcnt(" #n ")" ::: "memory")
; #define PG8_WAIT_L(n) asm volatile("s_waitcnt lgkmcnt(" #n ")" ::: "memory")
; #define PG8_BAR __builtin_amdgcn_s_barrier()
; #define PG8_SCHED __builtin_amdgcn_sched_barrier(0)
; template <class Epi>
; __device__ __forceinline__ void gemm_phase(LAS unsigned char* lds, const Gemm g, const StaticOrder& S, const Epi& E, int wv0) {
;     ...
;       PG8_BAR; PG8_WAIT_L(0); PG8_MMA(1, 0, At, B0); PG8_BAR; PG8_SCHED;
;       PG8_STAGE(PG8_SB(1, 1), b3 + hstepB, voffB);
;       PG8_WAIT_V(6); PG8_BAR; PG8_MMA(1, 1, At, B1); PG8_BAR;
;     }
;   __device__ __forceinline__ void emit(const EpiPre& q0, int row, int col, f32x4 a, f32x4 b, const f32x4 (&hb)[2][2], const float (&hs)[2][4], int ai_, int m_, int bj_) const {
;     ...
;       const int br = e.aux; const u32x4 gw = q.u0;
;       v[0] *= bf_lo(gw.x); v[1] *= bf_hi(gw.x); v[2] *= bf_lo(gw.y); v[3] *= bf_hi(gw.y);
;       v[4] *= bf_lo(gw.z); v[5] *= bf_hi(gw.z); v[6] *= bf_lo(gw.w); v[7] *= bf_hi(gw.w);
;       bf16_t* fa = (bf16_t*)e.facc + (size_t)row * DM + col;
;       if (br > 0) { const u32x4 pw = q.u1;
;         v[0] += bf_lo(pw.x); v[1] += bf_hi(pw.x); v[2] += bf_lo(pw.y); v[3] += bf_hi(pw.y); v[4] += bf_lo(pw.z); v[5] += bf_hi(pw.z); v[6] += bf_lo(pw.w); v[7] += bf_hi(pw.w); }
;       if (br == 2) store8bf((bf16_t*)e.out + (size_t)row * DM + col, v);
;       else store8bf(fa, v);
	s_waitcnt lgkmcnt(0)
	s_setprio 1
	s_waitcnt lgkmcnt(0)
	v_mfma_f32_16x16x32_bf16 v[60:63], v[130:133], v[146:149], v[60:63]
	v_mfma_f32_16x16x32_bf16 v[56:59], v[138:141], v[146:149], v[56:59]
	v_mfma_f32_16x16x32_bf16 v[48:51], v[130:133], v[164:167], v[48:51]
	v_mfma_f32_16x16x32_bf16 v[40:43], v[138:141], v[164:167], v[40:43]
	v_mfma_f32_16x16x32_bf16 v[32:35], v[130:133], v[176:179], v[32:35]
	v_mfma_f32_16x16x32_bf16 v[24:27], v[138:141], v[176:179], v[24:27]
	v_mfma_f32_16x16x32_bf16 v[16:19], v[130:133], v[184:187], v[16:19]
	v_mfma_f32_16x16x32_bf16 v[8:11], v[138:141], v[184:187], v[8:11]
	v_mfma_f32_16x16x32_bf16 v[60:63], v[134:137], v[160:163], v[60:63]
	v_mfma_f32_16x16x32_bf16 v[56:59], v[142:145], v[160:163], v[56:59]
	v_mfma_f32_16x16x32_bf16 v[48:51], v[134:137], v[168:171], v[48:51]
	v_mfma_f32_16x16x32_bf16 v[40:43], v[142:145], v[168:171], v[40:43]
	v_mfma_f32_16x16x32_bf16 v[32:35], v[134:137], v[180:183], v[32:35]
	v_mfma_f32_16x16x32_bf16 v[24:27], v[142:145], v[180:183], v[24:27]
	v_mfma_f32_16x16x32_bf16 v[16:19], v[134:137], v[188:191], v[16:19]
	v_mfma_f32_16x16x32_bf16 v[8:11], v[142:145], v[188:191], v[8:11]
	s_setprio 0
	s_barrier
	s_add_u32 s18, s20, 0x40080
	s_addc_u32 s19, s21, 0
	s_add_i32 s0, s22, s35
	v_lshl_add_u64 v[130:131], s[18:19], 0, v[96:97]
	s_mov_b32 m0, s0
	s_nop 0
	global_load_lds_dwordx4 v[130:131], off
	v_lshl_add_u64 v[130:131], s[18:19], 0, v[154:155]
	s_add_i32 m0, s0, 0x2000
	s_nop 0
	global_load_lds_dwordx4 v[130:131], off
	s_waitcnt vmcnt(6)
	s_barrier
	s_setprio 1
	v_mfma_f32_16x16x32_bf16 v[52:55], v[192:195], v[146:149], v[52:55]
	v_mfma_f32_16x16x32_bf16 v[44:47], v[200:203], v[146:149], v[44:47]
	v_mfma_f32_16x16x32_bf16 v[36:39], v[192:195], v[164:167], v[36:39]
	v_mfma_f32_16x16x32_bf16 v[28:31], v[200:203], v[164:167], v[28:31]
	v_mfma_f32_16x16x32_bf16 v[20:23], v[192:195], v[176:179], v[20:23]
	v_mfma_f32_16x16x32_bf16 v[12:15], v[200:203], v[176:179], v[12:15]
	v_mfma_f32_16x16x32_bf16 v[4:7], v[192:195], v[184:187], v[4:7]
	v_mfma_f32_16x16x32_bf16 v[0:3], v[200:203], v[184:187], v[0:3]
	v_mfma_f32_16x16x32_bf16 v[52:55], v[196:199], v[160:163], v[52:55]
	v_mfma_f32_16x16x32_bf16 v[44:47], v[204:207], v[160:163], v[44:47]
	v_mfma_f32_16x16x32_bf16 v[36:39], v[196:199], v[168:171], v[36:39]
	v_mfma_f32_16x16x32_bf16 v[28:31], v[204:207], v[168:171], v[28:31]
	v_mfma_f32_16x16x32_bf16 v[20:23], v[196:199], v[180:183], v[20:23]
	v_mfma_f32_16x16x32_bf16 v[12:15], v[204:207], v[180:183], v[12:15]
	v_mfma_f32_16x16x32_bf16 v[4:7], v[196:199], v[188:191], v[4:7]
	v_mfma_f32_16x16x32_bf16 v[0:3], v[204:207], v[188:191], v[0:3]
	s_setprio 0
	s_add_i32 s49, s49, 2
	s_add_u32 s47, s47, 0x100
	s_addc_u32 s48, s48, 0
	s_cmp_gt_u32 s49, 13
	s_mov_b64 s[18:19], s[4:5]
	s_barrier
	s_cbranch_scc0 .LBB0_981
	v_lshl_add_u32 v213, s1, 8, v172
	v_lshl_or_b32 v214, s45, 8, v174
	v_mul_u32_u24_e32 v212, 0x3000, v213
	v_lshlrev_b32_e32 v213, 12, v213
	v_lshl_add_u32 v212, v214, 1, v212
	v_lshl_add_u32 v213, v214, 1, v213
	v_add_u32_e32 v214, 0x0, v212
	global_load_dwordx4 v[130:133], v214, s[6:7]
	global_load_dwordx4 v[134:137], v214, s[6:7] offset:256
	v_add_u32_e32 v214, 0x30000, v212
	global_load_dwordx4 v[138:141], v214, s[6:7]
	global_load_dwordx4 v[142:145], v214, s[6:7] offset:256
	v_add_u32_e32 v214, 0x60000, v212
	global_load_dwordx4 v[146:149], v214, s[6:7]
	global_load_dwordx4 v[160:163], v214, s[6:7] offset:256
	v_add_u32_e32 v214, 0x90000, v212
	global_load_dwordx4 v[164:167], v214, s[6:7]
	global_load_dwordx4 v[168:171], v214, s[6:7] offset:256
	v_add_u32_e32 v214, 0x180000, v212
	global_load_dwordx4 v[176:179], v214, s[6:7]
	global_load_dwordx4 v[180:183], v214, s[6:7] offset:256
	v_add_u32_e32 v214, 0x1b0000, v212
	global_load_dwordx4 v[184:187], v214, s[6:7]
	global_load_dwordx4 v[188:191], v214, s[6:7] offset:256
	v_add_u32_e32 v214, 0x1e0000, v212
	global_load_dwordx4 v[192:195], v214, s[6:7]
	global_load_dwordx4 v[196:199], v214, s[6:7] offset:256
	v_add_u32_e32 v214, 0x210000, v212
	global_load_dwordx4 v[200:203], v214, s[6:7]
	global_load_dwordx4 v[204:207], v214, s[6:7] offset:256
	s_waitcnt vmcnt(15)
	v_lshlrev_b32_e32 v208, 16, v130
	v_and_b32_e32 v209, 0xffff0000, v130
	v_pk_mul_f32 v[126:127], v[126:127], v[208:209]
	v_lshlrev_b32_e32 v208, 16, v131
	v_and_b32_e32 v209, 0xffff0000, v131
	v_pk_mul_f32 v[128:129], v[128:129], v[208:209]
	v_lshlrev_b32_e32 v208, 16, v132
	v_and_b32_e32 v209, 0xffff0000, v132
	v_pk_mul_f32 v[122:123], v[122:123], v[208:209]
	v_lshlrev_b32_e32 v208, 16, v133
	v_and_b32_e32 v209, 0xffff0000, v133
	v_pk_mul_f32 v[124:125], v[124:125], v[208:209]
	v_cvt_pk_bf16_f32 v126, v126, v127
	v_cvt_pk_bf16_f32 v127, v128, v129
	v_cvt_pk_bf16_f32 v128, v122, v123
	v_cvt_pk_bf16_f32 v129, v124, v125
	v_add_u32_e32 v215, 0x0, v213
	global_store_dwordx4 v215, v[126:129], s[8:9]
	s_waitcnt vmcnt(15)
	v_lshlrev_b32_e32 v208, 16, v134
	v_and_b32_e32 v209, 0xffff0000, v134
	v_pk_mul_f32 v[114:115], v[114:115], v[208:209]
	v_lshlrev_b32_e32 v208, 16, v135
	v_and_b32_e32 v209, 0xffff0000, v135
	v_pk_mul_f32 v[116:117], v[116:117], v[208:209]
	v_lshlrev_b32_e32 v208, 16, v136
	v_and_b32_e32 v209, 0xffff0000, v136
	v_pk_mul_f32 v[106:107], v[106:107], v[208:209]
	v_lshlrev_b32_e32 v208, 16, v137
	v_and_b32_e32 v209, 0xffff0000, v137
	v_pk_mul_f32 v[108:109], v[108:109], v[208:209]
	v_cvt_pk_bf16_f32 v114, v114, v115
	v_cvt_pk_bf16_f32 v115, v116, v117
	v_cvt_pk_bf16_f32 v116, v106, v107
	v_cvt_pk_bf16_f32 v117, v108, v109
	global_store_dwordx4 v215, v[114:117], s[8:9] offset:256
	s_waitcnt vmcnt(15)
; __device__ __forceinline__ float bf_lo(unsigned u) { return __uint_as_float(u << 16); }
; __device__ __forceinline__ float bf_hi(unsigned u) { return __uint_as_float(u & 0xffff0000u); }
;   __device__ __forceinline__ void emit(const EpiPre& q0, int row, int col, f32x4 a, f32x4 b, const f32x4 (&hb)[2][2], const float (&hs)[2][4], int ai_, int m_, int bj_) const {
;     ...
;       const int br = e.aux; const u32x4 gw = q.u0;
;       v[0] *= bf_lo(gw.x); v[1] *= bf_hi(gw.x); v[2] *= bf_lo(gw.y); v[3] *= bf_hi(gw.y);
;       v[4] *= bf_lo(gw.z); v[5] *= bf_hi(gw.z); v[6] *= bf_lo(gw.w); v[7] *= bf_hi(gw.w);
;       bf16_t* fa = (bf16_t*)e.facc + (size_t)row * DM + col;
;       if (br > 0) { const u32x4 pw = q.u1;
;         v[0] += bf_lo(pw.x); v[1] += bf_hi(pw.x); v[2] += bf_lo(pw.y); v[3] += bf_hi(pw.y); v[4] += bf_lo(pw.z); v[5] += bf_hi(pw.z); v[6] += bf_lo(pw.w); v[7] += bf_hi(pw.w); }
;       if (br == 2) store8bf((bf16_t*)e.out + (size_t)row * DM + col, v);
;       else store8bf(fa, v);
	v_lshlrev_b32_e32 v208, 16, v138
	v_and_b32_e32 v209, 0xffff0000, v138
	v_pk_mul_f32 v[118:119], v[118:119], v[208:209]
	v_lshlrev_b32_e32 v208, 16, v139
	v_and_b32_e32 v209, 0xffff0000, v139
	v_pk_mul_f32 v[120:121], v[120:121], v[208:209]
	v_lshlrev_b32_e32 v208, 16, v140
	v_and_b32_e32 v209, 0xffff0000, v140
	v_pk_mul_f32 v[110:111], v[110:111], v[208:209]
	v_lshlrev_b32_e32 v208, 16, v141
	v_and_b32_e32 v209, 0xffff0000, v141
	v_pk_mul_f32 v[112:113], v[112:113], v[208:209]
	v_cvt_pk_bf16_f32 v118, v118, v119
	v_cvt_pk_bf16_f32 v119, v120, v121
	v_cvt_pk_bf16_f32 v120, v110, v111
	v_cvt_pk_bf16_f32 v121, v112, v113
	v_add_u32_e32 v215, 0x10000, v213
	global_store_dwordx4 v215, v[118:121], s[8:9]
	s_waitcnt vmcnt(15)
	v_lshlrev_b32_e32 v208, 16, v142
	v_and_b32_e32 v209, 0xffff0000, v142
	v_pk_mul_f32 v[102:103], v[102:103], v[208:209]
	v_lshlrev_b32_e32 v208, 16, v143
	v_and_b32_e32 v209, 0xffff0000, v143
	v_pk_mul_f32 v[104:105], v[104:105], v[208:209]
	v_lshlrev_b32_e32 v208, 16, v144
	v_and_b32_e32 v209, 0xffff0000, v144
	v_pk_mul_f32 v[98:99], v[98:99], v[208:209]
	v_lshlrev_b32_e32 v208, 16, v145
	v_and_b32_e32 v209, 0xffff0000, v145
	v_pk_mul_f32 v[100:101], v[100:101], v[208:209]
	v_cvt_pk_bf16_f32 v102, v102, v103
	v_cvt_pk_bf16_f32 v103, v104, v105
	v_cvt_pk_bf16_f32 v104, v98, v99
	v_cvt_pk_bf16_f32 v105, v100, v101
	global_store_dwordx4 v215, v[102:105], s[8:9] offset:256
	s_waitcnt vmcnt(15)
	v_lshlrev_b32_e32 v208, 16, v146
	v_and_b32_e32 v209, 0xffff0000, v146
	v_pk_mul_f32 v[92:93], v[92:93], v[208:209]
	v_lshlrev_b32_e32 v208, 16, v147
	v_and_b32_e32 v209, 0xffff0000, v147
	v_pk_mul_f32 v[94:95], v[94:95], v[208:209]
	v_lshlrev_b32_e32 v208, 16, v148
	v_and_b32_e32 v209, 0xffff0000, v148
	v_pk_mul_f32 v[88:89], v[88:89], v[208:209]
	v_lshlrev_b32_e32 v208, 16, v149
	v_and_b32_e32 v209, 0xffff0000, v149
	v_pk_mul_f32 v[90:91], v[90:91], v[208:209]
	v_cvt_pk_bf16_f32 v92, v92, v93
	v_cvt_pk_bf16_f32 v93, v94, v95
	v_cvt_pk_bf16_f32 v94, v88, v89
	v_cvt_pk_bf16_f32 v95, v90, v91
	v_add_u32_e32 v215, 0x20000, v213
	global_store_dwordx4 v215, v[92:95], s[8:9]
	s_waitcnt vmcnt(15)
	v_lshlrev_b32_e32 v208, 16, v160
	v_and_b32_e32 v209, 0xffff0000, v160
	v_pk_mul_f32 v[84:85], v[84:85], v[208:209]
	v_lshlrev_b32_e32 v208, 16, v161
	v_and_b32_e32 v209, 0xffff0000, v161
	v_pk_mul_f32 v[86:87], v[86:87], v[208:209]
	v_lshlrev_b32_e32 v208, 16, v162
	v_and_b32_e32 v209, 0xffff0000, v162
	v_pk_mul_f32 v[76:77], v[76:77], v[208:209]
	v_lshlrev_b32_e32 v208, 16, v163
	v_and_b32_e32 v209, 0xffff0000, v163
	v_pk_mul_f32 v[78:79], v[78:79], v[208:209]
	v_cvt_pk_bf16_f32 v84, v84, v85
	v_cvt_pk_bf16_f32 v85, v86, v87
	v_cvt_pk_bf16_f32 v86, v76, v77
	v_cvt_pk_bf16_f32 v87, v78, v79
	global_store_dwordx4 v215, v[84:87], s[8:9] offset:256
	s_waitcnt vmcnt(15)
	v_lshlrev_b32_e32 v208, 16, v164
	v_and_b32_e32 v209, 0xffff0000, v164
	v_pk_mul_f32 v[80:81], v[80:81], v[208:209]
	v_lshlrev_b32_e32 v208, 16, v165
	v_and_b32_e32 v209, 0xffff0000, v165
	v_pk_mul_f32 v[82:83], v[82:83], v[208:209]
	v_lshlrev_b32_e32 v208, 16, v166
	v_and_b32_e32 v209, 0xffff0000, v166
	v_pk_mul_f32 v[72:73], v[72:73], v[208:209]
	v_lshlrev_b32_e32 v208, 16, v167
	v_and_b32_e32 v209, 0xffff0000, v167
	v_pk_mul_f32 v[74:75], v[74:75], v[208:209]
	v_cvt_pk_bf16_f32 v80, v80, v81
	v_cvt_pk_bf16_f32 v81, v82, v83
	v_cvt_pk_bf16_f32 v82, v72, v73
	v_cvt_pk_bf16_f32 v83, v74, v75
	v_add_u32_e32 v215, 0x30000, v213
	global_store_dwordx4 v215, v[80:83], s[8:9]
	s_waitcnt vmcnt(15)
	v_lshlrev_b32_e32 v208, 16, v168
	v_and_b32_e32 v209, 0xffff0000, v168
	v_pk_mul_f32 v[68:69], v[68:69], v[208:209]
	v_lshlrev_b32_e32 v208, 16, v169
	v_and_b32_e32 v209, 0xffff0000, v169
	v_pk_mul_f32 v[70:71], v[70:71], v[208:209]
	v_lshlrev_b32_e32 v208, 16, v170
	v_and_b32_e32 v209, 0xffff0000, v170
	v_pk_mul_f32 v[64:65], v[64:65], v[208:209]
	v_lshlrev_b32_e32 v208, 16, v171
	v_and_b32_e32 v209, 0xffff0000, v171
	v_pk_mul_f32 v[66:67], v[66:67], v[208:209]
	v_cvt_pk_bf16_f32 v68, v68, v69
	v_cvt_pk_bf16_f32 v69, v70, v71
	v_cvt_pk_bf16_f32 v70, v64, v65
	v_cvt_pk_bf16_f32 v71, v66, v67
	global_store_dwordx4 v215, v[68:71], s[8:9] offset:256
	s_waitcnt vmcnt(15)
	v_lshlrev_b32_e32 v208, 16, v176
	v_and_b32_e32 v209, 0xffff0000, v176
	v_pk_mul_f32 v[60:61], v[60:61], v[208:209]
	v_lshlrev_b32_e32 v208, 16, v177
	v_and_b32_e32 v209, 0xffff0000, v177
	v_pk_mul_f32 v[62:63], v[62:63], v[208:209]
	v_lshlrev_b32_e32 v208, 16, v178
	v_and_b32_e32 v209, 0xffff0000, v178
	v_pk_mul_f32 v[56:57], v[56:57], v[208:209]
	v_lshlrev_b32_e32 v208, 16, v179
	v_and_b32_e32 v209, 0xffff0000, v179
	v_pk_mul_f32 v[58:59], v[58:59], v[208:209]
	v_cvt_pk_bf16_f32 v60, v60, v61
	v_cvt_pk_bf16_f32 v61, v62, v63
	v_cvt_pk_bf16_f32 v62, v56, v57
	v_cvt_pk_bf16_f32 v63, v58, v59
	v_add_u32_e32 v215, 0x80000, v213
	global_store_dwordx4 v215, v[60:63], s[8:9]
	s_waitcnt vmcnt(15)
; __device__ __forceinline__ float bf_lo(unsigned u) { return __uint_as_float(u << 16); }
; __device__ __forceinline__ float bf_hi(unsigned u) { return __uint_as_float(u & 0xffff0000u); }
;   __device__ __forceinline__ void emit(const EpiPre& q0, int row, int col, f32x4 a, f32x4 b, const f32x4 (&hb)[2][2], const float (&hs)[2][4], int ai_, int m_, int bj_) const {
;     ...
;       const int br = e.aux; const u32x4 gw = q.u0;
;       v[0] *= bf_lo(gw.x); v[1] *= bf_hi(gw.x); v[2] *= bf_lo(gw.y); v[3] *= bf_hi(gw.y);
;       v[4] *= bf_lo(gw.z); v[5] *= bf_hi(gw.z); v[6] *= bf_lo(gw.w); v[7] *= bf_hi(gw.w);
;       bf16_t* fa = (bf16_t*)e.facc + (size_t)row * DM + col;
;       if (br > 0) { const u32x4 pw = q.u1;
;         v[0] += bf_lo(pw.x); v[1] += bf_hi(pw.x); v[2] += bf_lo(pw.y); v[3] += bf_hi(pw.y); v[4] += bf_lo(pw.z); v[5] += bf_hi(pw.z); v[6] += bf_lo(pw.w); v[7] += bf_hi(pw.w); }
;       if (br == 2) store8bf((bf16_t*)e.out + (size_t)row * DM + col, v);
;       else store8bf(fa, v);
	v_lshlrev_b32_e32 v208, 16, v180
	v_and_b32_e32 v209, 0xffff0000, v180
	v_pk_mul_f32 v[52:53], v[52:53], v[208:209]
	v_lshlrev_b32_e32 v208, 16, v181
	v_and_b32_e32 v209, 0xffff0000, v181
	v_pk_mul_f32 v[54:55], v[54:55], v[208:209]
	v_lshlrev_b32_e32 v208, 16, v182
	v_and_b32_e32 v209, 0xffff0000, v182
	v_pk_mul_f32 v[44:45], v[44:45], v[208:209]
	v_lshlrev_b32_e32 v208, 16, v183
	v_and_b32_e32 v209, 0xffff0000, v183
	v_pk_mul_f32 v[46:47], v[46:47], v[208:209]
	v_cvt_pk_bf16_f32 v52, v52, v53
	v_cvt_pk_bf16_f32 v53, v54, v55
	v_cvt_pk_bf16_f32 v54, v44, v45
	v_cvt_pk_bf16_f32 v55, v46, v47
	global_store_dwordx4 v215, v[52:55], s[8:9] offset:256
	s_waitcnt vmcnt(15)
	v_lshlrev_b32_e32 v208, 16, v184
	v_and_b32_e32 v209, 0xffff0000, v184
	v_pk_mul_f32 v[48:49], v[48:49], v[208:209]
	v_lshlrev_b32_e32 v208, 16, v185
	v_and_b32_e32 v209, 0xffff0000, v185
	v_pk_mul_f32 v[50:51], v[50:51], v[208:209]
	v_lshlrev_b32_e32 v208, 16, v186
	v_and_b32_e32 v209, 0xffff0000, v186
	v_pk_mul_f32 v[40:41], v[40:41], v[208:209]
	v_lshlrev_b32_e32 v208, 16, v187
	v_and_b32_e32 v209, 0xffff0000, v187
	v_pk_mul_f32 v[42:43], v[42:43], v[208:209]
	v_cvt_pk_bf16_f32 v48, v48, v49
	v_cvt_pk_bf16_f32 v49, v50, v51
	v_cvt_pk_bf16_f32 v50, v40, v41
	v_cvt_pk_bf16_f32 v51, v42, v43
	v_add_u32_e32 v215, 0x90000, v213
	global_store_dwordx4 v215, v[48:51], s[8:9]
	s_waitcnt vmcnt(15)
	v_lshlrev_b32_e32 v208, 16, v188
	v_and_b32_e32 v209, 0xffff0000, v188
	v_pk_mul_f32 v[36:37], v[36:37], v[208:209]
	v_lshlrev_b32_e32 v208, 16, v189
	v_and_b32_e32 v209, 0xffff0000, v189
	v_pk_mul_f32 v[38:39], v[38:39], v[208:209]
	v_lshlrev_b32_e32 v208, 16, v190
	v_and_b32_e32 v209, 0xffff0000, v190
	v_pk_mul_f32 v[28:29], v[28:29], v[208:209]
	v_lshlrev_b32_e32 v208, 16, v191
	v_and_b32_e32 v209, 0xffff0000, v191
	v_pk_mul_f32 v[30:31], v[30:31], v[208:209]
	v_cvt_pk_bf16_f32 v36, v36, v37
	v_cvt_pk_bf16_f32 v37, v38, v39
	v_cvt_pk_bf16_f32 v38, v28, v29
	v_cvt_pk_bf16_f32 v39, v30, v31
	global_store_dwordx4 v215, v[36:39], s[8:9] offset:256
	s_waitcnt vmcnt(15)
	v_lshlrev_b32_e32 v208, 16, v192
	v_and_b32_e32 v209, 0xffff0000, v192
	v_pk_mul_f32 v[32:33], v[32:33], v[208:209]
	v_lshlrev_b32_e32 v208, 16, v193
	v_and_b32_e32 v209, 0xffff0000, v193
	v_pk_mul_f32 v[34:35], v[34:35], v[208:209]
	v_lshlrev_b32_e32 v208, 16, v194
	v_and_b32_e32 v209, 0xffff0000, v194
	v_pk_mul_f32 v[24:25], v[24:25], v[208:209]
	v_lshlrev_b32_e32 v208, 16, v195
	v_and_b32_e32 v209, 0xffff0000, v195
	v_pk_mul_f32 v[26:27], v[26:27], v[208:209]
	v_cvt_pk_bf16_f32 v32, v32, v33
	v_cvt_pk_bf16_f32 v33, v34, v35
	v_cvt_pk_bf16_f32 v34, v24, v25
	v_cvt_pk_bf16_f32 v35, v26, v27
	v_add_u32_e32 v215, 0xa0000, v213
	global_store_dwordx4 v215, v[32:35], s[8:9]
	s_waitcnt vmcnt(15)
	v_lshlrev_b32_e32 v208, 16, v196
	v_and_b32_e32 v209, 0xffff0000, v196
	v_pk_mul_f32 v[20:21], v[20:21], v[208:209]
	v_lshlrev_b32_e32 v208, 16, v197
	v_and_b32_e32 v209, 0xffff0000, v197
	v_pk_mul_f32 v[22:23], v[22:23], v[208:209]
	v_lshlrev_b32_e32 v208, 16, v198
	v_and_b32_e32 v209, 0xffff0000, v198
	v_pk_mul_f32 v[12:13], v[12:13], v[208:209]
	v_lshlrev_b32_e32 v208, 16, v199
	v_and_b32_e32 v209, 0xffff0000, v199
	v_pk_mul_f32 v[14:15], v[14:15], v[208:209]
	v_cvt_pk_bf16_f32 v20, v20, v21
	v_cvt_pk_bf16_f32 v21, v22, v23
	v_cvt_pk_bf16_f32 v22, v12, v13
	v_cvt_pk_bf16_f32 v23, v14, v15
	global_store_dwordx4 v215, v[20:23], s[8:9] offset:256
	s_waitcnt vmcnt(15)
	v_lshlrev_b32_e32 v208, 16, v200
	v_and_b32_e32 v209, 0xffff0000, v200
	v_pk_mul_f32 v[16:17], v[16:17], v[208:209]
	v_lshlrev_b32_e32 v208, 16, v201
	v_and_b32_e32 v209, 0xffff0000, v201
	v_pk_mul_f32 v[18:19], v[18:19], v[208:209]
	v_lshlrev_b32_e32 v208, 16, v202
	v_and_b32_e32 v209, 0xffff0000, v202
	v_pk_mul_f32 v[8:9], v[8:9], v[208:209]
	v_lshlrev_b32_e32 v208, 16, v203
	v_and_b32_e32 v209, 0xffff0000, v203
	v_pk_mul_f32 v[10:11], v[10:11], v[208:209]
	v_cvt_pk_bf16_f32 v16, v16, v17
	v_cvt_pk_bf16_f32 v17, v18, v19
	v_cvt_pk_bf16_f32 v18, v8, v9
	v_cvt_pk_bf16_f32 v19, v10, v11
	v_add_u32_e32 v215, 0xb0000, v213
	global_store_dwordx4 v215, v[16:19], s[8:9]
	s_waitcnt vmcnt(15)
	v_lshlrev_b32_e32 v208, 16, v204
	v_and_b32_e32 v209, 0xffff0000, v204
	v_pk_mul_f32 v[4:5], v[4:5], v[208:209]
	v_lshlrev_b32_e32 v208, 16, v205
	v_and_b32_e32 v209, 0xffff0000, v205
	v_pk_mul_f32 v[6:7], v[6:7], v[208:209]
	v_lshlrev_b32_e32 v208, 16, v206
	v_and_b32_e32 v209, 0xffff0000, v206
	v_pk_mul_f32 v[0:1], v[0:1], v[208:209]
	v_lshlrev_b32_e32 v208, 16, v207
	v_and_b32_e32 v209, 0xffff0000, v207
	v_pk_mul_f32 v[2:3], v[2:3], v[208:209]
	v_cvt_pk_bf16_f32 v4, v4, v5
	v_cvt_pk_bf16_f32 v5, v6, v7
	v_cvt_pk_bf16_f32 v6, v0, v1
	v_cvt_pk_bf16_f32 v7, v2, v3
	global_store_dwordx4 v215, v[4:7], s[8:9] offset:256
	s_mov_b32 s45, s12
	s_mov_b64 s[20:21], s[16:17]
	s_mov_b64 s[18:19], s[14:15]
	s_and_b64 vcc, exec, s[2:3]
	s_mov_b32 s1, s44
	s_cbranch_vccz .LBB0_972
	s_waitcnt vmcnt(0)
	s_cmpk_gt_u32 s27, 0xff
	s_cbranch_scc1 .LBB0_985
	s_barrier

; #define PG8_STAGE(bufoff, gbase, voff) do { _Pragma("unroll") for (int _i = 0; _i < 2; ++_i) \
;     __builtin_amdgcn_global_load_lds((const unsigned*)((const char*)(gbase) + (voff)[_i]), (LAS unsigned*)(lds + (bufoff) + ldsw + _i * 8192), 16, 0, 0); } while (0)
; #define PG8_LDA(dst, b, h) do { _Pragma("unroll") for (int m = 0; m < 4; ++m) _Pragma("unroll") for (int k = 0; k < 2; ++k) dst[m][k] = *(const LAS bf16x8*)(lds + PG8_SA(b, h) + aoff + m * 2048 + k * 1024); } while (0)
; #define PG8_LDB(dst, b, h) do { _Pragma("unroll") for (int n = 0; n < 2; ++n) _Pragma("unroll") for (int k = 0; k < 2; ++k) dst[n][k] = *(const LAS bf16x8*)(lds + PG8_SB(b, h) + boff + n * 2048 + k * 1024); } while (0)
; #define PG8_MMA(ai, bj, At, Bt) do { __builtin_amdgcn_s_setprio(1); _Pragma("unroll") for (int m = 0; m < 4; ++m) _Pragma("unroll") for (int n = 0; n < 2; ++n) _Pragma("unroll") for (int k = 0; k < 2; ++k) \
;     acc[ai][bj][m][n] = __builtin_amdgcn_mfma_f32_16x16x32_bf16(Bt[n][k], At[m][k], acc[ai][bj][m][n], 0, 0, 0); __builtin_amdgcn_s_setprio(0); } while (0)
; #define PG8_WAIT_L(n) asm volatile("s_waitcnt lgkmcnt(" #n ")" ::: "memory")
; #define PG8_BAR __builtin_amdgcn_s_barrier()
; #define PG8_SCHED __builtin_amdgcn_sched_barrier(0)
; template <class Epi>
; __device__ __forceinline__ void gemm_phase(LAS unsigned char* lds, const Gemm g, const StaticOrder& S, const Epi& E, int wv0) {
;     ...
;       PG8_LDB(B0, 0, 0); PG8_SCHED; PG8_LDA(At, 0, 0); PG8_STAGE(PG8_SA(1, 1), a1 + hstepA, voffA);
;       PG8_WAIT_L(8); PG8_BAR; PG8_WAIT_L(0); PG8_MMA(0, 0, At, B0); PG8_BAR; PG8_SCHED;
;       PG8_LDB(B1, 0, 1); PG8_STAGE(PG8_SB(0, 0), b2, voffB);
;       PG8_BAR; PG8_WAIT_L(0); PG8_MMA(0, 1, At, B1); PG8_BAR;
;       PG8_LDA(At, 0, 1); PG8_STAGE(PG8_SA(0, 0), a2, voffA);
;       PG8_BAR; PG8_WAIT_L(0); PG8_MMA(1, 0, At, B0); PG8_BAR; PG8_SCHED;
;       PG8_STAGE(PG8_SB(0, 1), b2 + hstepB, voffB);
.LBB0_1003:
	s_add_u32 s4, s18, 0x100
	s_addc_u32 s5, s19, 0
	s_add_i32 s0, 0, 0x10000
	v_add_u32_e32 v142, s0, v219
	ds_read_b128 v[130:133], v142
	ds_read_b128 v[134:137], v142 offset:1024
	ds_read_b128 v[138:141], v142 offset:2048
	ds_read_b128 v[142:145], v142 offset:3072
	s_cmp_eq_u32 s49, 28
	s_cselect_b32 s23, s15, s5
	s_cselect_b32 s22, s14, s4
	s_cselect_b32 s21, s13, s48
	s_cselect_b32 s20, s46, s47
	v_lshl_add_u64 v[178:179], s[18:19], 0, v[200:201]
	s_add_i32 m0, s36, 0xc000
	ds_read_b128 v[146:149], v225
	ds_read_b128 v[150:153], v225 offset:1024
	ds_read_b128 v[154:157], v225 offset:2048
	ds_read_b128 v[158:161], v225 offset:3072
	ds_read_b128 v[162:165], v225 offset:4096
	ds_read_b128 v[166:169], v225 offset:5120
	ds_read_b128 v[170:173], v225 offset:6144
	ds_read_b128 v[174:177], v225 offset:7168
	global_load_lds_dwordx4 v[178:179], off
	v_lshl_add_u64 v[178:179], s[18:19], 0, v[202:203]
	s_add_i32 m0, s36, 0xe000
	s_nop 0
	global_load_lds_dwordx4 v[178:179], off
	s_waitcnt lgkmcnt(8)
	s_barrier
	s_waitcnt lgkmcnt(0)
	s_setprio 1
	s_waitcnt lgkmcnt(0)
	v_mfma_f32_16x16x32_bf16 v[126:129], v[130:133], v[146:149], v[126:129]
	v_mfma_f32_16x16x32_bf16 v[122:125], v[138:141], v[146:149], v[122:125]
	v_mfma_f32_16x16x32_bf16 v[110:113], v[130:133], v[154:157], v[110:113]
	v_mfma_f32_16x16x32_bf16 v[106:109], v[138:141], v[154:157], v[106:109]
	v_mfma_f32_16x16x32_bf16 v[92:95], v[130:133], v[162:165], v[92:95]
	v_mfma_f32_16x16x32_bf16 v[88:91], v[138:141], v[162:165], v[88:91]
	v_mfma_f32_16x16x32_bf16 v[76:79], v[130:133], v[170:173], v[76:79]
	v_mfma_f32_16x16x32_bf16 v[72:75], v[138:141], v[170:173], v[72:75]
	v_mfma_f32_16x16x32_bf16 v[126:129], v[134:137], v[150:153], v[126:129]
	v_mfma_f32_16x16x32_bf16 v[122:125], v[142:145], v[150:153], v[122:125]
	v_mfma_f32_16x16x32_bf16 v[110:113], v[134:137], v[158:161], v[110:113]
	v_mfma_f32_16x16x32_bf16 v[106:109], v[142:145], v[158:161], v[106:109]
	v_mfma_f32_16x16x32_bf16 v[92:95], v[134:137], v[166:169], v[92:95]
	v_mfma_f32_16x16x32_bf16 v[88:91], v[142:145], v[166:169], v[88:91]
	v_mfma_f32_16x16x32_bf16 v[76:79], v[134:137], v[174:177], v[76:79]
	v_mfma_f32_16x16x32_bf16 v[72:75], v[142:145], v[174:177], v[72:75]
	s_setprio 0
	s_barrier
	s_add_i32 s50, 0, 0x14000
	s_add_i32 s0, s0, s35
	v_add_u32_e32 v190, s50, v219
	v_lshl_add_u64 v[204:205], s[20:21], 0, v[96:97]
	s_mov_b32 m0, s0
	ds_read_b128 v[178:181], v190
	ds_read_b128 v[182:185], v190 offset:1024
	ds_read_b128 v[186:189], v190 offset:2048
	ds_read_b128 v[190:193], v190 offset:3072
	global_load_lds_dwordx4 v[204:205], off
	v_lshl_add_u64 v[206:207], s[20:21], 0, v[198:199]
	s_add_i32 m0, s0, 0x2000
	s_nop 0
	global_load_lds_dwordx4 v[206:207], off
	s_barrier
	s_waitcnt lgkmcnt(0)
	s_setprio 1
	s_waitcnt lgkmcnt(0)
	v_mfma_f32_16x16x32_bf16 v[118:121], v[178:181], v[146:149], v[118:121]
	v_mfma_f32_16x16x32_bf16 v[114:117], v[186:189], v[146:149], v[114:117]
	v_mfma_f32_16x16x32_bf16 v[102:105], v[178:181], v[154:157], v[102:105]
	v_mfma_f32_16x16x32_bf16 v[98:101], v[186:189], v[154:157], v[98:101]
	v_mfma_f32_16x16x32_bf16 v[84:87], v[178:181], v[162:165], v[84:87]
	v_mfma_f32_16x16x32_bf16 v[80:83], v[186:189], v[162:165], v[80:83]
	v_mfma_f32_16x16x32_bf16 v[68:71], v[178:181], v[170:173], v[68:71]
	v_mfma_f32_16x16x32_bf16 v[64:67], v[186:189], v[170:173], v[64:67]
	v_mfma_f32_16x16x32_bf16 v[118:121], v[182:185], v[150:153], v[118:121]
	v_mfma_f32_16x16x32_bf16 v[114:117], v[190:193], v[150:153], v[114:117]
	v_mfma_f32_16x16x32_bf16 v[102:105], v[182:185], v[158:161], v[102:105]
	v_mfma_f32_16x16x32_bf16 v[98:101], v[190:193], v[158:161], v[98:101]
	v_mfma_f32_16x16x32_bf16 v[84:87], v[182:185], v[166:169], v[84:87]
	v_mfma_f32_16x16x32_bf16 v[80:83], v[190:193], v[166:169], v[80:83]
	v_mfma_f32_16x16x32_bf16 v[68:71], v[182:185], v[174:177], v[68:71]
	v_mfma_f32_16x16x32_bf16 v[64:67], v[190:193], v[174:177], v[64:67]
	s_setprio 0
	s_mov_b32 m0, s36
	v_lshl_add_u64 v[208:209], s[22:23], 0, v[194:195]
	s_barrier
	ds_read_b128 v[146:149], v225 offset:16384
	ds_read_b128 v[150:153], v225 offset:17408
	ds_read_b128 v[154:157], v225 offset:18432
	ds_read_b128 v[158:161], v225 offset:19456
	ds_read_b128 v[162:165], v225 offset:20480
	ds_read_b128 v[166:169], v225 offset:21504
	ds_read_b128 v[170:173], v225 offset:22528
	ds_read_b128 v[174:177], v225 offset:23552
	global_load_lds_dwordx4 v[208:209], off
	v_lshl_add_u64 v[210:211], s[22:23], 0, v[196:197]
	s_mov_b32 m0, s37
	s_nop 0
	global_load_lds_dwordx4 v[210:211], off
	s_barrier
	s_waitcnt lgkmcnt(0)
	s_setprio 1
	s_waitcnt lgkmcnt(0)
	v_mfma_f32_16x16x32_bf16 v[60:63], v[130:133], v[146:149], v[60:63]
	v_mfma_f32_16x16x32_bf16 v[56:59], v[138:141], v[146:149], v[56:59]
	v_mfma_f32_16x16x32_bf16 v[44:47], v[130:133], v[154:157], v[44:47]
	v_mfma_f32_16x16x32_bf16 v[40:43], v[138:141], v[154:157], v[40:43]
	v_mfma_f32_16x16x32_bf16 v[28:31], v[130:133], v[162:165], v[28:31]
	v_mfma_f32_16x16x32_bf16 v[24:27], v[138:141], v[162:165], v[24:27]
	v_mfma_f32_16x16x32_bf16 v[12:15], v[130:133], v[170:173], v[12:15]
	v_mfma_f32_16x16x32_bf16 v[8:11], v[138:141], v[170:173], v[8:11]
	v_mfma_f32_16x16x32_bf16 v[60:63], v[134:137], v[150:153], v[60:63]
	v_mfma_f32_16x16x32_bf16 v[56:59], v[142:145], v[150:153], v[56:59]
	v_mfma_f32_16x16x32_bf16 v[44:47], v[134:137], v[158:161], v[44:47]
	v_mfma_f32_16x16x32_bf16 v[40:43], v[142:145], v[158:161], v[40:43]
	v_mfma_f32_16x16x32_bf16 v[28:31], v[134:137], v[166:169], v[28:31]
	v_mfma_f32_16x16x32_bf16 v[24:27], v[142:145], v[166:169], v[24:27]
	v_mfma_f32_16x16x32_bf16 v[12:15], v[134:137], v[174:177], v[12:15]
	v_mfma_f32_16x16x32_bf16 v[8:11], v[142:145], v[174:177], v[8:11]
	s_setprio 0
	s_barrier
; #define PG8_STAGE(bufoff, gbase, voff) do { _Pragma("unroll") for (int _i = 0; _i < 2; ++_i) \
;     __builtin_amdgcn_global_load_lds((const unsigned*)((const char*)(gbase) + (voff)[_i]), (LAS unsigned*)(lds + (bufoff) + ldsw + _i * 8192), 16, 0, 0); } while (0)
; #define PG8_LDA(dst, b, h) do { _Pragma("unroll") for (int m = 0; m < 4; ++m) _Pragma("unroll") for (int k = 0; k < 2; ++k) dst[m][k] = *(const LAS bf16x8*)(lds + PG8_SA(b, h) + aoff + m * 2048 + k * 1024); } while (0)
; #define PG8_LDB(dst, b, h) do { _Pragma("unroll") for (int n = 0; n < 2; ++n) _Pragma("unroll") for (int k = 0; k < 2; ++k) dst[n][k] = *(const LAS bf16x8*)(lds + PG8_SB(b, h) + boff + n * 2048 + k * 1024); } while (0)
; #define PG8_MMA(ai, bj, At, Bt) do { __builtin_amdgcn_s_setprio(1); _Pragma("unroll") for (int m = 0; m < 4; ++m) _Pragma("unroll") for (int n = 0; n < 2; ++n) _Pragma("unroll") for (int k = 0; k < 2; ++k) \
;     acc[ai][bj][m][n] = __builtin_amdgcn_mfma_f32_16x16x32_bf16(Bt[n][k], At[m][k], acc[ai][bj][m][n], 0, 0, 0); __builtin_amdgcn_s_setprio(0); } while (0)
; template <class Epi>
; __device__ __forceinline__ void gemm_phase(LAS unsigned char* lds, const Gemm g, const StaticOrder& S, const Epi& E, int wv0) {
;     ...
;       PG8_LDB(B0, 0, 0); PG8_SCHED; PG8_LDA(At, 0, 0); PG8_STAGE(PG8_SA(1, 1), a1 + hstepA, voffA);
;       PG8_WAIT_L(8); PG8_BAR; PG8_WAIT_L(0); PG8_MMA(0, 0, At, B0); PG8_BAR; PG8_SCHED;
;       PG8_LDB(B1, 0, 1); PG8_STAGE(PG8_SB(0, 0), b2, voffB);
;       PG8_BAR; PG8_WAIT_L(0); PG8_MMA(0, 1, At, B1); PG8_BAR;
;       PG8_LDA(At, 0, 1); PG8_STAGE(PG8_SA(0, 0), a2, voffA);
;       PG8_BAR; PG8_WAIT_L(0); PG8_MMA(1, 0, At, B0); PG8_BAR; PG8_SCHED;
;       PG8_STAGE(PG8_SB(0, 1), b2 + hstepB, voffB);
;       PG8_WAIT_V(6); PG8_BAR; PG8_MMA(1, 1, At, B1); PG8_BAR;
;       PG8_LDB(B0, 1, 0); PG8_SCHED; PG8_LDA(At, 1, 0); PG8_STAGE(PG8_SA(0, 1), a2 + hstepA, voffA);
;       PG8_WAIT_L(8); PG8_BAR; PG8_WAIT_L(0); PG8_MMA(0, 0, At, B0); PG8_BAR; PG8_SCHED;
;       PG8_LDB(B1, 1, 1); PG8_STAGE(PG8_SB(1, 0), b3, voffB);
;       PG8_BAR; PG8_WAIT_L(0); PG8_MMA(0, 1, At, B1); PG8_BAR;
;       PG8_LDA(At, 1, 1); PG8_STAGE(PG8_SA(1, 0), a3, voffA);
;       PG8_BAR; PG8_WAIT_L(0); PG8_MMA(1, 0, At, B0); PG8_BAR; PG8_SCHED;
;       PG8_STAGE(PG8_SB(1, 1), b3 + hstepB, voffB);
;       PG8_WAIT_V(6); PG8_BAR; PG8_MMA(1, 1, At, B1); PG8_BAR;
	s_add_u32 s18, s20, 0x80000
	s_addc_u32 s19, s21, 0
	s_add_i32 s0, s50, s35
	v_lshl_add_u64 v[130:131], s[18:19], 0, v[96:97]
	s_mov_b32 m0, s0
	s_nop 0
	global_load_lds_dwordx4 v[130:131], off
	v_lshl_add_u64 v[130:131], s[18:19], 0, v[198:199]
	s_add_i32 m0, s0, 0x2000
	s_nop 0
	global_load_lds_dwordx4 v[130:131], off
	s_waitcnt vmcnt(6)
	s_barrier
	s_setprio 1
	v_mfma_f32_16x16x32_bf16 v[52:55], v[178:181], v[146:149], v[52:55]
	v_mfma_f32_16x16x32_bf16 v[48:51], v[186:189], v[146:149], v[48:51]
	v_mfma_f32_16x16x32_bf16 v[36:39], v[178:181], v[154:157], v[36:39]
	v_mfma_f32_16x16x32_bf16 v[32:35], v[186:189], v[154:157], v[32:35]
	v_mfma_f32_16x16x32_bf16 v[20:23], v[178:181], v[162:165], v[20:23]
	v_mfma_f32_16x16x32_bf16 v[16:19], v[186:189], v[162:165], v[16:19]
	v_mfma_f32_16x16x32_bf16 v[4:7], v[178:181], v[170:173], v[4:7]
	v_mfma_f32_16x16x32_bf16 v[0:3], v[186:189], v[170:173], v[0:3]
	v_mfma_f32_16x16x32_bf16 v[52:55], v[182:185], v[150:153], v[52:55]
	v_mfma_f32_16x16x32_bf16 v[48:51], v[190:193], v[150:153], v[48:51]
	v_mfma_f32_16x16x32_bf16 v[36:39], v[182:185], v[158:161], v[36:39]
	v_mfma_f32_16x16x32_bf16 v[32:35], v[190:193], v[158:161], v[32:35]
	v_mfma_f32_16x16x32_bf16 v[20:23], v[182:185], v[166:169], v[20:23]
	v_mfma_f32_16x16x32_bf16 v[16:19], v[190:193], v[166:169], v[16:19]
	v_mfma_f32_16x16x32_bf16 v[4:7], v[182:185], v[174:177], v[4:7]
	v_mfma_f32_16x16x32_bf16 v[0:3], v[190:193], v[174:177], v[0:3]
	s_setprio 0
	s_add_i32 s0, 0, 0x18000
	v_add_u32_e32 v142, s0, v219
	s_barrier
	ds_read_b128 v[130:133], v142
	ds_read_b128 v[134:137], v142 offset:1024
	ds_read_b128 v[138:141], v142 offset:2048
	ds_read_b128 v[142:145], v142 offset:3072
	s_add_u32 s18, s22, 0x114000
	s_addc_u32 s19, s23, 0
	s_mov_b32 m0, s38
	v_lshl_add_u64 v[178:179], s[18:19], 0, v[194:195]
	ds_read_b128 v[146:149], v225 offset:32768
	ds_read_b128 v[150:153], v225 offset:33792
	ds_read_b128 v[154:157], v225 offset:34816
	ds_read_b128 v[158:161], v225 offset:35840
	ds_read_b128 v[162:165], v225 offset:36864
	ds_read_b128 v[166:169], v225 offset:37888
	ds_read_b128 v[170:173], v225 offset:38912
	ds_read_b128 v[174:177], v225 offset:39936
	global_load_lds_dwordx4 v[178:179], off
	v_lshl_add_u64 v[178:179], s[18:19], 0, v[196:197]
	s_mov_b32 m0, s39
	s_nop 0
	global_load_lds_dwordx4 v[178:179], off
	s_waitcnt lgkmcnt(8)
	s_barrier
	s_waitcnt lgkmcnt(0)
	s_setprio 1
	s_waitcnt lgkmcnt(0)
	v_mfma_f32_16x16x32_bf16 v[126:129], v[130:133], v[146:149], v[126:129]
	v_mfma_f32_16x16x32_bf16 v[122:125], v[138:141], v[146:149], v[122:125]
	v_mfma_f32_16x16x32_bf16 v[110:113], v[130:133], v[154:157], v[110:113]
	v_mfma_f32_16x16x32_bf16 v[106:109], v[138:141], v[154:157], v[106:109]
	v_mfma_f32_16x16x32_bf16 v[92:95], v[130:133], v[162:165], v[92:95]
	v_mfma_f32_16x16x32_bf16 v[88:91], v[138:141], v[162:165], v[88:91]
	v_mfma_f32_16x16x32_bf16 v[76:79], v[130:133], v[170:173], v[76:79]
	v_mfma_f32_16x16x32_bf16 v[72:75], v[138:141], v[170:173], v[72:75]
	v_mfma_f32_16x16x32_bf16 v[126:129], v[134:137], v[150:153], v[126:129]
	v_mfma_f32_16x16x32_bf16 v[122:125], v[142:145], v[150:153], v[122:125]
	v_mfma_f32_16x16x32_bf16 v[110:113], v[134:137], v[158:161], v[110:113]
	v_mfma_f32_16x16x32_bf16 v[106:109], v[142:145], v[158:161], v[106:109]
	v_mfma_f32_16x16x32_bf16 v[92:95], v[134:137], v[166:169], v[92:95]
	v_mfma_f32_16x16x32_bf16 v[88:91], v[142:145], v[166:169], v[88:91]
	v_mfma_f32_16x16x32_bf16 v[76:79], v[134:137], v[174:177], v[76:79]
	v_mfma_f32_16x16x32_bf16 v[72:75], v[142:145], v[174:177], v[72:75]
	s_setprio 0
	s_barrier
	s_add_i32 s22, 0, 0x1c000
	s_add_i32 s0, s0, s35
	v_add_u32_e32 v190, s22, v219
	v_lshl_add_u64 v[204:205], v[204:205], 0, s[72:73]
	s_mov_b32 m0, s0
	ds_read_b128 v[178:181], v190
	ds_read_b128 v[182:185], v190 offset:1024
	ds_read_b128 v[186:189], v190 offset:2048
	ds_read_b128 v[190:193], v190 offset:3072
	global_load_lds_dwordx4 v[204:205], off
	v_lshl_add_u64 v[204:205], v[206:207], 0, s[72:73]
	s_add_i32 m0, s0, 0x2000
	s_nop 0
	global_load_lds_dwordx4 v[204:205], off
	s_barrier
	s_waitcnt lgkmcnt(0)
	s_setprio 1
	s_waitcnt lgkmcnt(0)
	v_mfma_f32_16x16x32_bf16 v[118:121], v[178:181], v[146:149], v[118:121]
	v_mfma_f32_16x16x32_bf16 v[114:117], v[186:189], v[146:149], v[114:117]
	v_mfma_f32_16x16x32_bf16 v[102:105], v[178:181], v[154:157], v[102:105]
	v_mfma_f32_16x16x32_bf16 v[98:101], v[186:189], v[154:157], v[98:101]
	v_mfma_f32_16x16x32_bf16 v[84:87], v[178:181], v[162:165], v[84:87]
	v_mfma_f32_16x16x32_bf16 v[80:83], v[186:189], v[162:165], v[80:83]
	v_mfma_f32_16x16x32_bf16 v[68:71], v[178:181], v[170:173], v[68:71]
	v_mfma_f32_16x16x32_bf16 v[64:67], v[186:189], v[170:173], v[64:67]
	v_mfma_f32_16x16x32_bf16 v[118:121], v[182:185], v[150:153], v[118:121]
	v_mfma_f32_16x16x32_bf16 v[114:117], v[190:193], v[150:153], v[114:117]
	v_mfma_f32_16x16x32_bf16 v[102:105], v[182:185], v[158:161], v[102:105]
	v_mfma_f32_16x16x32_bf16 v[98:101], v[190:193], v[158:161], v[98:101]
	v_mfma_f32_16x16x32_bf16 v[84:87], v[182:185], v[166:169], v[84:87]
	v_mfma_f32_16x16x32_bf16 v[80:83], v[190:193], v[166:169], v[80:83]
	v_mfma_f32_16x16x32_bf16 v[68:71], v[182:185], v[174:177], v[68:71]
	v_mfma_f32_16x16x32_bf16 v[64:67], v[190:193], v[174:177], v[64:67]
	s_setprio 0
	s_mov_b32 m0, s40
	v_lshl_add_u64 v[204:205], v[208:209], 0, s[72:73]
	s_barrier
	ds_read_b128 v[146:149], v225 offset:49152
	ds_read_b128 v[150:153], v225 offset:50176
	ds_read_b128 v[154:157], v225 offset:51200
	ds_read_b128 v[158:161], v225 offset:52224
	ds_read_b128 v[162:165], v225 offset:53248
	ds_read_b128 v[166:169], v225 offset:54272
	ds_read_b128 v[170:173], v225 offset:55296
	ds_read_b128 v[174:177], v225 offset:56320
	global_load_lds_dwordx4 v[204:205], off
	v_lshl_add_u64 v[204:205], v[210:211], 0, s[72:73]
	s_mov_b32 m0, s41
	s_nop 0
	global_load_lds_dwordx4 v[204:205], off
	s_barrier
; __device__ __forceinline__ float bf_lo(unsigned u) { return __uint_as_float(u << 16); }
; __device__ __forceinline__ float bf_hi(unsigned u) { return __uint_as_float(u & 0xffff0000u); }
; #define PG8_STAGE(bufoff, gbase, voff) do { _Pragma("unroll") for (int _i = 0; _i < 2; ++_i) \
;     __builtin_amdgcn_global_load_lds((const unsigned*)((const char*)(gbase) + (voff)[_i]), (LAS unsigned*)(lds + (bufoff) + ldsw + _i * 8192), 16, 0, 0); } while (0)
; #define PG8_LDA(dst, b, h) do { _Pragma("unroll") for (int m = 0; m < 4; ++m) _Pragma("unroll") for (int k = 0; k < 2; ++k) dst[m][k] = *(const LAS bf16x8*)(lds + PG8_SA(b, h) + aoff + m * 2048 + k * 1024); } while (0)
; #define PG8_WAIT_V(n) asm volatile("s_waitcnt vmcnt(" #n ")" ::: "memory")
; template <class Epi>
; __device__ __forceinline__ void gemm_phase(LAS unsigned char* lds, const Gemm g, const StaticOrder& S, const Epi& E, int wv0) {
;     ...
;       PG8_BAR; PG8_WAIT_L(0); PG8_MMA(0, 1, At, B1); PG8_BAR;
;       PG8_LDA(At, 1, 1); PG8_STAGE(PG8_SA(1, 0), a3, voffA);
;       PG8_BAR; PG8_WAIT_L(0); PG8_MMA(1, 0, At, B0); PG8_BAR; PG8_SCHED;
;       PG8_STAGE(PG8_SB(1, 1), b3 + hstepB, voffB);
;       PG8_WAIT_V(6); PG8_BAR; PG8_MMA(1, 1, At, B1); PG8_BAR;
;     }
;   __device__ __forceinline__ void preload(EpiPre& q, int row, int col) const {
;     ...
;     } else if (MODE == E_PROJ) {
;       q.u0 = *(const u32x4*)(e.b0 + (size_t)row * NG + e.aux * DM + col);
;       if (e.aux > 0) q.u1 = *(const u32x4*)((const bf16_t*)e.facc + (size_t)row * DM + col);
;   __device__ __forceinline__ void emit(const EpiPre& q0, int row, int col, f32x4 a, f32x4 b, const f32x4 (&hb)[2][2], const float (&hs)[2][4], int ai_, int m_, int bj_) const {
;     ...
;     } else if (MODE == E_PROJ) {
;       const int br = e.aux; const u32x4 gw = q.u0;
;       v[0] *= bf_lo(gw.x); v[1] *= bf_hi(gw.x); v[2] *= bf_lo(gw.y); v[3] *= bf_hi(gw.y);
;       v[4] *= bf_lo(gw.z); v[5] *= bf_hi(gw.z); v[6] *= bf_lo(gw.w); v[7] *= bf_hi(gw.w);
;       bf16_t* fa = (bf16_t*)e.facc + (size_t)row * DM + col;
;       if (br > 0) { const u32x4 pw = q.u1;
;         v[0] += bf_lo(pw.x); v[1] += bf_hi(pw.x); v[2] += bf_lo(pw.y); v[3] += bf_hi(pw.y); v[4] += bf_lo(pw.z); v[5] += bf_hi(pw.z); v[6] += bf_lo(pw.w); v[7] += bf_hi(pw.w); }
;       if (br == 2) store8bf((bf16_t*)e.out + (size_t)row * DM + col, v);
;       else store8bf(fa, v);
	s_waitcnt lgkmcnt(0)
	s_setprio 1
	s_waitcnt lgkmcnt(0)
	v_mfma_f32_16x16x32_bf16 v[60:63], v[130:133], v[146:149], v[60:63]
	v_mfma_f32_16x16x32_bf16 v[56:59], v[138:141], v[146:149], v[56:59]
	v_mfma_f32_16x16x32_bf16 v[44:47], v[130:133], v[154:157], v[44:47]
	v_mfma_f32_16x16x32_bf16 v[40:43], v[138:141], v[154:157], v[40:43]
	v_mfma_f32_16x16x32_bf16 v[28:31], v[130:133], v[162:165], v[28:31]
	v_mfma_f32_16x16x32_bf16 v[24:27], v[138:141], v[162:165], v[24:27]
	v_mfma_f32_16x16x32_bf16 v[12:15], v[130:133], v[170:173], v[12:15]
	v_mfma_f32_16x16x32_bf16 v[8:11], v[138:141], v[170:173], v[8:11]
	v_mfma_f32_16x16x32_bf16 v[60:63], v[134:137], v[150:153], v[60:63]
	v_mfma_f32_16x16x32_bf16 v[56:59], v[142:145], v[150:153], v[56:59]
	v_mfma_f32_16x16x32_bf16 v[44:47], v[134:137], v[158:161], v[44:47]
	v_mfma_f32_16x16x32_bf16 v[40:43], v[142:145], v[158:161], v[40:43]
	v_mfma_f32_16x16x32_bf16 v[28:31], v[134:137], v[166:169], v[28:31]
	v_mfma_f32_16x16x32_bf16 v[24:27], v[142:145], v[166:169], v[24:27]
	v_mfma_f32_16x16x32_bf16 v[12:15], v[134:137], v[174:177], v[12:15]
	v_mfma_f32_16x16x32_bf16 v[8:11], v[142:145], v[174:177], v[8:11]
	s_setprio 0
	s_barrier
	s_add_u32 s18, s20, 0x80080
	s_addc_u32 s19, s21, 0
	s_add_i32 s0, s22, s35
	v_lshl_add_u64 v[130:131], s[18:19], 0, v[96:97]
	s_mov_b32 m0, s0
	s_nop 0
	global_load_lds_dwordx4 v[130:131], off
	v_lshl_add_u64 v[130:131], s[18:19], 0, v[198:199]
	s_add_i32 m0, s0, 0x2000
	s_nop 0
	global_load_lds_dwordx4 v[130:131], off
	s_waitcnt vmcnt(6)
	s_barrier
	s_setprio 1
	v_mfma_f32_16x16x32_bf16 v[52:55], v[178:181], v[146:149], v[52:55]
	v_mfma_f32_16x16x32_bf16 v[48:51], v[186:189], v[146:149], v[48:51]
	v_mfma_f32_16x16x32_bf16 v[36:39], v[178:181], v[154:157], v[36:39]
	v_mfma_f32_16x16x32_bf16 v[32:35], v[186:189], v[154:157], v[32:35]
	v_mfma_f32_16x16x32_bf16 v[20:23], v[178:181], v[162:165], v[20:23]
	v_mfma_f32_16x16x32_bf16 v[16:19], v[186:189], v[162:165], v[16:19]
	v_mfma_f32_16x16x32_bf16 v[4:7], v[178:181], v[170:173], v[4:7]
	v_mfma_f32_16x16x32_bf16 v[0:3], v[186:189], v[170:173], v[0:3]
	v_mfma_f32_16x16x32_bf16 v[52:55], v[182:185], v[150:153], v[52:55]
	v_mfma_f32_16x16x32_bf16 v[48:51], v[190:193], v[150:153], v[48:51]
	v_mfma_f32_16x16x32_bf16 v[36:39], v[182:185], v[158:161], v[36:39]
	v_mfma_f32_16x16x32_bf16 v[32:35], v[190:193], v[158:161], v[32:35]
	v_mfma_f32_16x16x32_bf16 v[20:23], v[182:185], v[166:169], v[20:23]
	v_mfma_f32_16x16x32_bf16 v[16:19], v[190:193], v[166:169], v[16:19]
	v_mfma_f32_16x16x32_bf16 v[4:7], v[182:185], v[174:177], v[4:7]
	v_mfma_f32_16x16x32_bf16 v[0:3], v[190:193], v[174:177], v[0:3]
	s_setprio 0
	s_add_i32 s49, s49, 2
	s_add_u32 s47, s47, 0x100
	s_addc_u32 s48, s48, 0
	s_cmp_gt_u32 s49, 29
	s_mov_b64 s[18:19], s[4:5]
	s_barrier
	s_cbranch_scc0 .LBB0_1003
	v_lshl_add_u32 v209, s1, 8, v218
	v_lshl_or_b32 v211, s45, 8, v224
	v_mul_u32_u24_e32 v208, 0x3000, v209
	v_lshlrev_b32_e32 v209, 12, v209
	v_lshl_add_u32 v208, v211, 1, v208
	v_lshl_add_u32 v209, v211, 1, v209
	v_add_u32_e32 v211, 0x0, v208
	global_load_dwordx4 v[130:133], v211, s[8:9]
	v_add_u32_e32 v212, 0x0, v209
	global_load_dwordx4 v[134:137], v212, s[6:7]
	global_load_dwordx4 v[138:141], v211, s[8:9] offset:256
	global_load_dwordx4 v[142:145], v212, s[6:7] offset:256
	v_add_u32_e32 v211, 0x30000, v208
	global_load_dwordx4 v[146:149], v211, s[8:9]
	v_add_u32_e32 v212, 0x10000, v209
	global_load_dwordx4 v[150:153], v212, s[6:7]
	global_load_dwordx4 v[154:157], v211, s[8:9] offset:256
	global_load_dwordx4 v[158:161], v212, s[6:7] offset:256
	v_add_u32_e32 v211, 0x60000, v208
	global_load_dwordx4 v[162:165], v211, s[8:9]
	v_add_u32_e32 v212, 0x20000, v209
	global_load_dwordx4 v[166:169], v212, s[6:7]
	global_load_dwordx4 v[170:173], v211, s[8:9] offset:256
	global_load_dwordx4 v[174:177], v212, s[6:7] offset:256
	v_add_u32_e32 v211, 0x90000, v208
	global_load_dwordx4 v[178:181], v211, s[8:9]
	v_add_u32_e32 v212, 0x30000, v209
	global_load_dwordx4 v[182:185], v212, s[6:7]
	global_load_dwordx4 v[186:189], v211, s[8:9] offset:256
	global_load_dwordx4 v[190:193], v212, s[6:7] offset:256
	s_waitcnt vmcnt(14)
	v_lshlrev_b32_e32 v204, 16, v130
	v_and_b32_e32 v205, 0xffff0000, v130
	v_lshlrev_b32_e32 v206, 16, v134
	v_and_b32_e32 v207, 0xffff0000, v134
	v_pk_fma_f32 v[126:127], v[126:127], v[204:205], v[206:207]
	v_lshlrev_b32_e32 v204, 16, v131
	v_and_b32_e32 v205, 0xffff0000, v131
	v_lshlrev_b32_e32 v206, 16, v135
	v_and_b32_e32 v207, 0xffff0000, v135
	v_pk_fma_f32 v[128:129], v[128:129], v[204:205], v[206:207]
	v_lshlrev_b32_e32 v204, 16, v132
	v_and_b32_e32 v205, 0xffff0000, v132
	v_lshlrev_b32_e32 v206, 16, v136
	v_and_b32_e32 v207, 0xffff0000, v136
	v_pk_fma_f32 v[122:123], v[122:123], v[204:205], v[206:207]
	v_lshlrev_b32_e32 v204, 16, v133
	v_and_b32_e32 v205, 0xffff0000, v133
	v_lshlrev_b32_e32 v206, 16, v137
	v_and_b32_e32 v207, 0xffff0000, v137
	v_pk_fma_f32 v[124:125], v[124:125], v[204:205], v[206:207]
	v_cvt_pk_bf16_f32 v126, v126, v127
	v_cvt_pk_bf16_f32 v127, v128, v129
	v_cvt_pk_bf16_f32 v128, v122, v123
	v_cvt_pk_bf16_f32 v129, v124, v125
	v_add_u32_e32 v211, 0x180000, v208
	global_load_dwordx4 v[130:133], v211, s[8:9]
	v_add_u32_e32 v212, 0x80000, v209
	global_load_dwordx4 v[134:137], v212, s[6:7]
	s_waitcnt vmcnt(14)
; __device__ __forceinline__ float bf_lo(unsigned u) { return __uint_as_float(u << 16); }
; __device__ __forceinline__ float bf_hi(unsigned u) { return __uint_as_float(u & 0xffff0000u); }
;   __device__ __forceinline__ void preload(EpiPre& q, int row, int col) const {
;     ...
;     } else if (MODE == E_PROJ) {
;       q.u0 = *(const u32x4*)(e.b0 + (size_t)row * NG + e.aux * DM + col);
;       if (e.aux > 0) q.u1 = *(const u32x4*)((const bf16_t*)e.facc + (size_t)row * DM + col);
;   __device__ __forceinline__ void emit(const EpiPre& q0, int row, int col, f32x4 a, f32x4 b, const f32x4 (&hb)[2][2], const float (&hs)[2][4], int ai_, int m_, int bj_) const {
;     ...
;     } else if (MODE == E_PROJ) {
;       const int br = e.aux; const u32x4 gw = q.u0;
;       v[0] *= bf_lo(gw.x); v[1] *= bf_hi(gw.x); v[2] *= bf_lo(gw.y); v[3] *= bf_hi(gw.y);
;       v[4] *= bf_lo(gw.z); v[5] *= bf_hi(gw.z); v[6] *= bf_lo(gw.w); v[7] *= bf_hi(gw.w);
;       bf16_t* fa = (bf16_t*)e.facc + (size_t)row * DM + col;
;       if (br > 0) { const u32x4 pw = q.u1;
;         v[0] += bf_lo(pw.x); v[1] += bf_hi(pw.x); v[2] += bf_lo(pw.y); v[3] += bf_hi(pw.y); v[4] += bf_lo(pw.z); v[5] += bf_hi(pw.z); v[6] += bf_lo(pw.w); v[7] += bf_hi(pw.w); }
;       if (br == 2) store8bf((bf16_t*)e.out + (size_t)row * DM + col, v);
;       else store8bf(fa, v);
	v_lshlrev_b32_e32 v204, 16, v138
	v_and_b32_e32 v205, 0xffff0000, v138
	v_lshlrev_b32_e32 v206, 16, v142
	v_and_b32_e32 v207, 0xffff0000, v142
	v_pk_fma_f32 v[118:119], v[118:119], v[204:205], v[206:207]
	v_lshlrev_b32_e32 v204, 16, v139
	v_and_b32_e32 v205, 0xffff0000, v139
	v_lshlrev_b32_e32 v206, 16, v143
	v_and_b32_e32 v207, 0xffff0000, v143
	v_pk_fma_f32 v[120:121], v[120:121], v[204:205], v[206:207]
	v_lshlrev_b32_e32 v204, 16, v140
	v_and_b32_e32 v205, 0xffff0000, v140
	v_lshlrev_b32_e32 v206, 16, v144
	v_and_b32_e32 v207, 0xffff0000, v144
	v_pk_fma_f32 v[114:115], v[114:115], v[204:205], v[206:207]
	v_lshlrev_b32_e32 v204, 16, v141
	v_and_b32_e32 v205, 0xffff0000, v141
	v_lshlrev_b32_e32 v206, 16, v145
	v_and_b32_e32 v207, 0xffff0000, v145
	v_pk_fma_f32 v[116:117], v[116:117], v[204:205], v[206:207]
	v_cvt_pk_bf16_f32 v118, v118, v119
	v_cvt_pk_bf16_f32 v119, v120, v121
	v_cvt_pk_bf16_f32 v120, v114, v115
	v_cvt_pk_bf16_f32 v121, v116, v117
	global_load_dwordx4 v[138:141], v211, s[8:9] offset:256
	global_load_dwordx4 v[142:145], v212, s[6:7] offset:256
	s_waitcnt vmcnt(14)
	v_lshlrev_b32_e32 v204, 16, v146
	v_and_b32_e32 v205, 0xffff0000, v146
	v_lshlrev_b32_e32 v206, 16, v150
	v_and_b32_e32 v207, 0xffff0000, v150
	v_pk_fma_f32 v[110:111], v[110:111], v[204:205], v[206:207]
	v_lshlrev_b32_e32 v204, 16, v147
	v_and_b32_e32 v205, 0xffff0000, v147
	v_lshlrev_b32_e32 v206, 16, v151
	v_and_b32_e32 v207, 0xffff0000, v151
	v_pk_fma_f32 v[112:113], v[112:113], v[204:205], v[206:207]
	v_lshlrev_b32_e32 v204, 16, v148
	v_and_b32_e32 v205, 0xffff0000, v148
	v_lshlrev_b32_e32 v206, 16, v152
	v_and_b32_e32 v207, 0xffff0000, v152
	v_pk_fma_f32 v[106:107], v[106:107], v[204:205], v[206:207]
	v_lshlrev_b32_e32 v204, 16, v149
	v_and_b32_e32 v205, 0xffff0000, v149
	v_lshlrev_b32_e32 v206, 16, v153
	v_and_b32_e32 v207, 0xffff0000, v153
	v_pk_fma_f32 v[108:109], v[108:109], v[204:205], v[206:207]
	v_cvt_pk_bf16_f32 v110, v110, v111
	v_cvt_pk_bf16_f32 v111, v112, v113
	v_cvt_pk_bf16_f32 v112, v106, v107
	v_cvt_pk_bf16_f32 v113, v108, v109
	v_add_u32_e32 v211, 0x1b0000, v208
	global_load_dwordx4 v[146:149], v211, s[8:9]
	v_add_u32_e32 v212, 0x90000, v209
	global_load_dwordx4 v[150:153], v212, s[6:7]
	s_waitcnt vmcnt(14)
	v_lshlrev_b32_e32 v204, 16, v154
	v_and_b32_e32 v205, 0xffff0000, v154
	v_lshlrev_b32_e32 v206, 16, v158
	v_and_b32_e32 v207, 0xffff0000, v158
	v_pk_fma_f32 v[102:103], v[102:103], v[204:205], v[206:207]
	v_lshlrev_b32_e32 v204, 16, v155
	v_and_b32_e32 v205, 0xffff0000, v155
	v_lshlrev_b32_e32 v206, 16, v159
	v_and_b32_e32 v207, 0xffff0000, v159
	v_pk_fma_f32 v[104:105], v[104:105], v[204:205], v[206:207]
	v_lshlrev_b32_e32 v204, 16, v156
	v_and_b32_e32 v205, 0xffff0000, v156
	v_lshlrev_b32_e32 v206, 16, v160
	v_and_b32_e32 v207, 0xffff0000, v160
	v_pk_fma_f32 v[98:99], v[98:99], v[204:205], v[206:207]
	v_lshlrev_b32_e32 v204, 16, v157
	v_and_b32_e32 v205, 0xffff0000, v157
	v_lshlrev_b32_e32 v206, 16, v161
	v_and_b32_e32 v207, 0xffff0000, v161
	v_pk_fma_f32 v[100:101], v[100:101], v[204:205], v[206:207]
	v_cvt_pk_bf16_f32 v102, v102, v103
	v_cvt_pk_bf16_f32 v103, v104, v105
	v_cvt_pk_bf16_f32 v104, v98, v99
	v_cvt_pk_bf16_f32 v105, v100, v101
	global_load_dwordx4 v[154:157], v211, s[8:9] offset:256
	global_load_dwordx4 v[158:161], v212, s[6:7] offset:256
	s_waitcnt vmcnt(14)
	v_lshlrev_b32_e32 v204, 16, v162
	v_and_b32_e32 v205, 0xffff0000, v162
	v_lshlrev_b32_e32 v206, 16, v166
	v_and_b32_e32 v207, 0xffff0000, v166
	v_pk_fma_f32 v[92:93], v[92:93], v[204:205], v[206:207]
	v_lshlrev_b32_e32 v204, 16, v163
	v_and_b32_e32 v205, 0xffff0000, v163
	v_lshlrev_b32_e32 v206, 16, v167
	v_and_b32_e32 v207, 0xffff0000, v167
	v_pk_fma_f32 v[94:95], v[94:95], v[204:205], v[206:207]
	v_lshlrev_b32_e32 v204, 16, v164
	v_and_b32_e32 v205, 0xffff0000, v164
	v_lshlrev_b32_e32 v206, 16, v168
	v_and_b32_e32 v207, 0xffff0000, v168
	v_pk_fma_f32 v[88:89], v[88:89], v[204:205], v[206:207]
	v_lshlrev_b32_e32 v204, 16, v165
	v_and_b32_e32 v205, 0xffff0000, v165
	v_lshlrev_b32_e32 v206, 16, v169
	v_and_b32_e32 v207, 0xffff0000, v169
	v_pk_fma_f32 v[90:91], v[90:91], v[204:205], v[206:207]
	v_cvt_pk_bf16_f32 v92, v92, v93
	v_cvt_pk_bf16_f32 v93, v94, v95
	v_cvt_pk_bf16_f32 v94, v88, v89
	v_cvt_pk_bf16_f32 v95, v90, v91
	v_add_u32_e32 v211, 0x1e0000, v208
	global_load_dwordx4 v[162:165], v211, s[8:9]
	v_add_u32_e32 v212, 0xa0000, v209
	global_load_dwordx4 v[166:169], v212, s[6:7]
	s_waitcnt vmcnt(14)
	v_lshlrev_b32_e32 v204, 16, v170
	v_and_b32_e32 v205, 0xffff0000, v170
	v_lshlrev_b32_e32 v206, 16, v174
	v_and_b32_e32 v207, 0xffff0000, v174
	v_pk_fma_f32 v[84:85], v[84:85], v[204:205], v[206:207]
	v_lshlrev_b32_e32 v204, 16, v171
	v_and_b32_e32 v205, 0xffff0000, v171
	v_lshlrev_b32_e32 v206, 16, v175
	v_and_b32_e32 v207, 0xffff0000, v175
	v_pk_fma_f32 v[86:87], v[86:87], v[204:205], v[206:207]
	v_lshlrev_b32_e32 v204, 16, v172
	v_and_b32_e32 v205, 0xffff0000, v172
	v_lshlrev_b32_e32 v206, 16, v176
	v_and_b32_e32 v207, 0xffff0000, v176
	v_pk_fma_f32 v[80:81], v[80:81], v[204:205], v[206:207]
	v_lshlrev_b32_e32 v204, 16, v173
	v_and_b32_e32 v205, 0xffff0000, v173
	v_lshlrev_b32_e32 v206, 16, v177
	v_and_b32_e32 v207, 0xffff0000, v177
	v_pk_fma_f32 v[82:83], v[82:83], v[204:205], v[206:207]
	v_cvt_pk_bf16_f32 v84, v84, v85
	v_cvt_pk_bf16_f32 v85, v86, v87
	v_cvt_pk_bf16_f32 v86, v80, v81
	v_cvt_pk_bf16_f32 v87, v82, v83
	global_load_dwordx4 v[170:173], v211, s[8:9] offset:256
	global_load_dwordx4 v[174:177], v212, s[6:7] offset:256
	s_waitcnt vmcnt(14)
; __device__ __forceinline__ float bf_lo(unsigned u) { return __uint_as_float(u << 16); }
; __device__ __forceinline__ float bf_hi(unsigned u) { return __uint_as_float(u & 0xffff0000u); }
;   __device__ __forceinline__ void emit(const EpiPre& q0, int row, int col, f32x4 a, f32x4 b, const f32x4 (&hb)[2][2], const float (&hs)[2][4], int ai_, int m_, int bj_) const {
;     ...
;     } else if (MODE == E_PROJ) {
;       const int br = e.aux; const u32x4 gw = q.u0;
;       v[0] *= bf_lo(gw.x); v[1] *= bf_hi(gw.x); v[2] *= bf_lo(gw.y); v[3] *= bf_hi(gw.y);
;       v[4] *= bf_lo(gw.z); v[5] *= bf_hi(gw.z); v[6] *= bf_lo(gw.w); v[7] *= bf_hi(gw.w);
;       bf16_t* fa = (bf16_t*)e.facc + (size_t)row * DM + col;
;       if (br > 0) { const u32x4 pw = q.u1;
;         v[0] += bf_lo(pw.x); v[1] += bf_hi(pw.x); v[2] += bf_lo(pw.y); v[3] += bf_hi(pw.y); v[4] += bf_lo(pw.z); v[5] += bf_hi(pw.z); v[6] += bf_lo(pw.w); v[7] += bf_hi(pw.w); }
;       if (br == 2) store8bf((bf16_t*)e.out + (size_t)row * DM + col, v);
;       else store8bf(fa, v);
	v_lshlrev_b32_e32 v204, 16, v178
	v_and_b32_e32 v205, 0xffff0000, v178
	v_lshlrev_b32_e32 v206, 16, v182
	v_and_b32_e32 v207, 0xffff0000, v182
	v_pk_fma_f32 v[76:77], v[76:77], v[204:205], v[206:207]
	v_lshlrev_b32_e32 v204, 16, v179
	v_and_b32_e32 v205, 0xffff0000, v179
	v_lshlrev_b32_e32 v206, 16, v183
	v_and_b32_e32 v207, 0xffff0000, v183
	v_pk_fma_f32 v[78:79], v[78:79], v[204:205], v[206:207]
	v_lshlrev_b32_e32 v204, 16, v180
	v_and_b32_e32 v205, 0xffff0000, v180
	v_lshlrev_b32_e32 v206, 16, v184
	v_and_b32_e32 v207, 0xffff0000, v184
	v_pk_fma_f32 v[72:73], v[72:73], v[204:205], v[206:207]
	v_lshlrev_b32_e32 v204, 16, v181
	v_and_b32_e32 v205, 0xffff0000, v181
	v_lshlrev_b32_e32 v206, 16, v185
	v_and_b32_e32 v207, 0xffff0000, v185
	v_pk_fma_f32 v[74:75], v[74:75], v[204:205], v[206:207]
	v_cvt_pk_bf16_f32 v76, v76, v77
	v_cvt_pk_bf16_f32 v77, v78, v79
	v_cvt_pk_bf16_f32 v78, v72, v73
	v_cvt_pk_bf16_f32 v79, v74, v75
	v_add_u32_e32 v211, 0x210000, v208
	global_load_dwordx4 v[178:181], v211, s[8:9]
	v_add_u32_e32 v212, 0xb0000, v209
	global_load_dwordx4 v[182:185], v212, s[6:7]
	s_waitcnt vmcnt(14)
	v_lshlrev_b32_e32 v204, 16, v186
	v_and_b32_e32 v205, 0xffff0000, v186
	v_lshlrev_b32_e32 v206, 16, v190
	v_and_b32_e32 v207, 0xffff0000, v190
	v_pk_fma_f32 v[68:69], v[68:69], v[204:205], v[206:207]
	v_lshlrev_b32_e32 v204, 16, v187
	v_and_b32_e32 v205, 0xffff0000, v187
	v_lshlrev_b32_e32 v206, 16, v191
	v_and_b32_e32 v207, 0xffff0000, v191
	v_pk_fma_f32 v[70:71], v[70:71], v[204:205], v[206:207]
	v_lshlrev_b32_e32 v204, 16, v188
	v_and_b32_e32 v205, 0xffff0000, v188
	v_lshlrev_b32_e32 v206, 16, v192
	v_and_b32_e32 v207, 0xffff0000, v192
	v_pk_fma_f32 v[64:65], v[64:65], v[204:205], v[206:207]
	v_lshlrev_b32_e32 v204, 16, v189
	v_and_b32_e32 v205, 0xffff0000, v189
	v_lshlrev_b32_e32 v206, 16, v193
	v_and_b32_e32 v207, 0xffff0000, v193
	v_pk_fma_f32 v[66:67], v[66:67], v[204:205], v[206:207]
	v_cvt_pk_bf16_f32 v68, v68, v69
	v_cvt_pk_bf16_f32 v69, v70, v71
	v_cvt_pk_bf16_f32 v70, v64, v65
	v_cvt_pk_bf16_f32 v71, v66, v67
	global_load_dwordx4 v[186:189], v211, s[8:9] offset:256
	global_load_dwordx4 v[190:193], v212, s[6:7] offset:256
	v_add_u32_e32 v212, 0x0, v209
	global_store_dwordx4 v212, v[126:129], s[6:7]
	global_store_dwordx4 v212, v[118:121], s[6:7] offset:256
	v_add_u32_e32 v212, 0x10000, v209
	global_store_dwordx4 v212, v[110:113], s[6:7]
	global_store_dwordx4 v212, v[102:105], s[6:7] offset:256
	v_add_u32_e32 v212, 0x20000, v209
	global_store_dwordx4 v212, v[92:95], s[6:7]
	global_store_dwordx4 v212, v[84:87], s[6:7] offset:256
	v_add_u32_e32 v212, 0x30000, v209
	global_store_dwordx4 v212, v[76:79], s[6:7]
	global_store_dwordx4 v212, v[68:71], s[6:7] offset:256
	s_waitcnt vmcnt(22)
	v_lshlrev_b32_e32 v204, 16, v130
	v_and_b32_e32 v205, 0xffff0000, v130
	v_lshlrev_b32_e32 v206, 16, v134
	v_and_b32_e32 v207, 0xffff0000, v134
	v_pk_fma_f32 v[60:61], v[60:61], v[204:205], v[206:207]
	v_lshlrev_b32_e32 v204, 16, v131
	v_and_b32_e32 v205, 0xffff0000, v131
	v_lshlrev_b32_e32 v206, 16, v135
	v_and_b32_e32 v207, 0xffff0000, v135
	v_pk_fma_f32 v[62:63], v[62:63], v[204:205], v[206:207]
	v_lshlrev_b32_e32 v204, 16, v132
	v_and_b32_e32 v205, 0xffff0000, v132
	v_lshlrev_b32_e32 v206, 16, v136
	v_and_b32_e32 v207, 0xffff0000, v136
	v_pk_fma_f32 v[56:57], v[56:57], v[204:205], v[206:207]
	v_lshlrev_b32_e32 v204, 16, v133
	v_and_b32_e32 v205, 0xffff0000, v133
	v_lshlrev_b32_e32 v206, 16, v137
	v_and_b32_e32 v207, 0xffff0000, v137
	v_pk_fma_f32 v[58:59], v[58:59], v[204:205], v[206:207]
	v_cvt_pk_bf16_f32 v60, v60, v61
	v_cvt_pk_bf16_f32 v61, v62, v63
	v_cvt_pk_bf16_f32 v62, v56, v57
	v_cvt_pk_bf16_f32 v63, v58, v59
	v_add_u32_e32 v212, 0x80000, v209
	global_store_dwordx4 v212, v[60:63], s[6:7]
	s_waitcnt vmcnt(21)
	v_lshlrev_b32_e32 v204, 16, v138
	v_and_b32_e32 v205, 0xffff0000, v138
	v_lshlrev_b32_e32 v206, 16, v142
	v_and_b32_e32 v207, 0xffff0000, v142
	v_pk_fma_f32 v[52:53], v[52:53], v[204:205], v[206:207]
	v_lshlrev_b32_e32 v204, 16, v139
	v_and_b32_e32 v205, 0xffff0000, v139
	v_lshlrev_b32_e32 v206, 16, v143
	v_and_b32_e32 v207, 0xffff0000, v143
	v_pk_fma_f32 v[54:55], v[54:55], v[204:205], v[206:207]
	v_lshlrev_b32_e32 v204, 16, v140
	v_and_b32_e32 v205, 0xffff0000, v140
	v_lshlrev_b32_e32 v206, 16, v144
	v_and_b32_e32 v207, 0xffff0000, v144
	v_pk_fma_f32 v[48:49], v[48:49], v[204:205], v[206:207]
	v_lshlrev_b32_e32 v204, 16, v141
	v_and_b32_e32 v205, 0xffff0000, v141
	v_lshlrev_b32_e32 v206, 16, v145
	v_and_b32_e32 v207, 0xffff0000, v145
	v_pk_fma_f32 v[50:51], v[50:51], v[204:205], v[206:207]
	v_cvt_pk_bf16_f32 v52, v52, v53
	v_cvt_pk_bf16_f32 v53, v54, v55
	v_cvt_pk_bf16_f32 v54, v48, v49
	v_cvt_pk_bf16_f32 v55, v50, v51
	global_store_dwordx4 v212, v[52:55], s[6:7] offset:256
	s_waitcnt vmcnt(20)
	v_lshlrev_b32_e32 v204, 16, v146
	v_and_b32_e32 v205, 0xffff0000, v146
	v_lshlrev_b32_e32 v206, 16, v150
	v_and_b32_e32 v207, 0xffff0000, v150
	v_pk_fma_f32 v[44:45], v[44:45], v[204:205], v[206:207]
	v_lshlrev_b32_e32 v204, 16, v147
	v_and_b32_e32 v205, 0xffff0000, v147
	v_lshlrev_b32_e32 v206, 16, v151
	v_and_b32_e32 v207, 0xffff0000, v151
	v_pk_fma_f32 v[46:47], v[46:47], v[204:205], v[206:207]
	v_lshlrev_b32_e32 v204, 16, v148
	v_and_b32_e32 v205, 0xffff0000, v148
	v_lshlrev_b32_e32 v206, 16, v152
	v_and_b32_e32 v207, 0xffff0000, v152
	v_pk_fma_f32 v[40:41], v[40:41], v[204:205], v[206:207]
	v_lshlrev_b32_e32 v204, 16, v149
	v_and_b32_e32 v205, 0xffff0000, v149
	v_lshlrev_b32_e32 v206, 16, v153
	v_and_b32_e32 v207, 0xffff0000, v153
	v_pk_fma_f32 v[42:43], v[42:43], v[204:205], v[206:207]
	v_cvt_pk_bf16_f32 v44, v44, v45
	v_cvt_pk_bf16_f32 v45, v46, v47
	v_cvt_pk_bf16_f32 v46, v40, v41
	v_cvt_pk_bf16_f32 v47, v42, v43
	v_add_u32_e32 v212, 0x90000, v209
	global_store_dwordx4 v212, v[44:47], s[6:7]
	s_waitcnt vmcnt(19)
; __device__ __forceinline__ float bf_lo(unsigned u) { return __uint_as_float(u << 16); }
; __device__ __forceinline__ float bf_hi(unsigned u) { return __uint_as_float(u & 0xffff0000u); }
; template <class Epi>
; __device__ __forceinline__ void gemm_phase(LAS unsigned char* lds, const Gemm g, const StaticOrder& S, const Epi& E, int wv0) {
;     ...
;     E(acc, cur, wr, wc, fr, fq);
;     if (!has_next) break;
; #pragma unroll
;     for (int a = 0; a < 2; ++a)
; #pragma unroll
;       for (int b = 0; b < 2; ++b)
; #pragma unroll
;         for (int m = 0; m < 4; ++m)
; #pragma unroll
;           for (int n = 0; n < 2; ++n) acc[a][b][m][n] = (f32x4){0.f, 0.f, 0.f, 0.f};
;     cur = nxt; cA = nA; cB = nB; ++ui;
;   }
;   __device__ __forceinline__ void emit(const EpiPre& q0, int row, int col, f32x4 a, f32x4 b, const f32x4 (&hb)[2][2], const float (&hs)[2][4], int ai_, int m_, int bj_) const {
;     ...
;     } else if (MODE == E_PROJ) {
;       const int br = e.aux; const u32x4 gw = q.u0;
;       v[0] *= bf_lo(gw.x); v[1] *= bf_hi(gw.x); v[2] *= bf_lo(gw.y); v[3] *= bf_hi(gw.y);
;       v[4] *= bf_lo(gw.z); v[5] *= bf_hi(gw.z); v[6] *= bf_lo(gw.w); v[7] *= bf_hi(gw.w);
;       bf16_t* fa = (bf16_t*)e.facc + (size_t)row * DM + col;
;       if (br > 0) { const u32x4 pw = q.u1;
;         v[0] += bf_lo(pw.x); v[1] += bf_hi(pw.x); v[2] += bf_lo(pw.y); v[3] += bf_hi(pw.y); v[4] += bf_lo(pw.z); v[5] += bf_hi(pw.z); v[6] += bf_lo(pw.w); v[7] += bf_hi(pw.w); }
;       if (br == 2) store8bf((bf16_t*)e.out + (size_t)row * DM + col, v);
;       else store8bf(fa, v);
	v_lshlrev_b32_e32 v204, 16, v154
	v_and_b32_e32 v205, 0xffff0000, v154
	v_lshlrev_b32_e32 v206, 16, v158
	v_and_b32_e32 v207, 0xffff0000, v158
	v_pk_fma_f32 v[36:37], v[36:37], v[204:205], v[206:207]
	v_lshlrev_b32_e32 v204, 16, v155
	v_and_b32_e32 v205, 0xffff0000, v155
	v_lshlrev_b32_e32 v206, 16, v159
	v_and_b32_e32 v207, 0xffff0000, v159
	v_pk_fma_f32 v[38:39], v[38:39], v[204:205], v[206:207]
	v_lshlrev_b32_e32 v204, 16, v156
	v_and_b32_e32 v205, 0xffff0000, v156
	v_lshlrev_b32_e32 v206, 16, v160
	v_and_b32_e32 v207, 0xffff0000, v160
	v_pk_fma_f32 v[32:33], v[32:33], v[204:205], v[206:207]
	v_lshlrev_b32_e32 v204, 16, v157
	v_and_b32_e32 v205, 0xffff0000, v157
	v_lshlrev_b32_e32 v206, 16, v161
	v_and_b32_e32 v207, 0xffff0000, v161
	v_pk_fma_f32 v[34:35], v[34:35], v[204:205], v[206:207]
	v_cvt_pk_bf16_f32 v36, v36, v37
	v_cvt_pk_bf16_f32 v37, v38, v39
	v_cvt_pk_bf16_f32 v38, v32, v33
	v_cvt_pk_bf16_f32 v39, v34, v35
	global_store_dwordx4 v212, v[36:39], s[6:7] offset:256
	s_waitcnt vmcnt(18)
	v_lshlrev_b32_e32 v204, 16, v162
	v_and_b32_e32 v205, 0xffff0000, v162
	v_lshlrev_b32_e32 v206, 16, v166
	v_and_b32_e32 v207, 0xffff0000, v166
	v_pk_fma_f32 v[28:29], v[28:29], v[204:205], v[206:207]
	v_lshlrev_b32_e32 v204, 16, v163
	v_and_b32_e32 v205, 0xffff0000, v163
	v_lshlrev_b32_e32 v206, 16, v167
	v_and_b32_e32 v207, 0xffff0000, v167
	v_pk_fma_f32 v[30:31], v[30:31], v[204:205], v[206:207]
	v_lshlrev_b32_e32 v204, 16, v164
	v_and_b32_e32 v205, 0xffff0000, v164
	v_lshlrev_b32_e32 v206, 16, v168
	v_and_b32_e32 v207, 0xffff0000, v168
	v_pk_fma_f32 v[24:25], v[24:25], v[204:205], v[206:207]
	v_lshlrev_b32_e32 v204, 16, v165
	v_and_b32_e32 v205, 0xffff0000, v165
	v_lshlrev_b32_e32 v206, 16, v169
	v_and_b32_e32 v207, 0xffff0000, v169
	v_pk_fma_f32 v[26:27], v[26:27], v[204:205], v[206:207]
	v_cvt_pk_bf16_f32 v28, v28, v29
	v_cvt_pk_bf16_f32 v29, v30, v31
	v_cvt_pk_bf16_f32 v30, v24, v25
	v_cvt_pk_bf16_f32 v31, v26, v27
	v_add_u32_e32 v212, 0xa0000, v209
	global_store_dwordx4 v212, v[28:31], s[6:7]
	s_waitcnt vmcnt(17)
	v_lshlrev_b32_e32 v204, 16, v170
	v_and_b32_e32 v205, 0xffff0000, v170
	v_lshlrev_b32_e32 v206, 16, v174
	v_and_b32_e32 v207, 0xffff0000, v174
	v_pk_fma_f32 v[20:21], v[20:21], v[204:205], v[206:207]
	v_lshlrev_b32_e32 v204, 16, v171
	v_and_b32_e32 v205, 0xffff0000, v171
	v_lshlrev_b32_e32 v206, 16, v175
	v_and_b32_e32 v207, 0xffff0000, v175
	v_pk_fma_f32 v[22:23], v[22:23], v[204:205], v[206:207]
	v_lshlrev_b32_e32 v204, 16, v172
	v_and_b32_e32 v205, 0xffff0000, v172
	v_lshlrev_b32_e32 v206, 16, v176
	v_and_b32_e32 v207, 0xffff0000, v176
	v_pk_fma_f32 v[16:17], v[16:17], v[204:205], v[206:207]
	v_lshlrev_b32_e32 v204, 16, v173
	v_and_b32_e32 v205, 0xffff0000, v173
	v_lshlrev_b32_e32 v206, 16, v177
	v_and_b32_e32 v207, 0xffff0000, v177
	v_pk_fma_f32 v[18:19], v[18:19], v[204:205], v[206:207]
	v_cvt_pk_bf16_f32 v20, v20, v21
	v_cvt_pk_bf16_f32 v21, v22, v23
	v_cvt_pk_bf16_f32 v22, v16, v17
	v_cvt_pk_bf16_f32 v23, v18, v19
	global_store_dwordx4 v212, v[20:23], s[6:7] offset:256
	s_waitcnt vmcnt(16)
	v_lshlrev_b32_e32 v204, 16, v178
	v_and_b32_e32 v205, 0xffff0000, v178
	v_lshlrev_b32_e32 v206, 16, v182
	v_and_b32_e32 v207, 0xffff0000, v182
	v_pk_fma_f32 v[12:13], v[12:13], v[204:205], v[206:207]
	v_lshlrev_b32_e32 v204, 16, v179
	v_and_b32_e32 v205, 0xffff0000, v179
	v_lshlrev_b32_e32 v206, 16, v183
	v_and_b32_e32 v207, 0xffff0000, v183
	v_pk_fma_f32 v[14:15], v[14:15], v[204:205], v[206:207]
	v_lshlrev_b32_e32 v204, 16, v180
	v_and_b32_e32 v205, 0xffff0000, v180
	v_lshlrev_b32_e32 v206, 16, v184
	v_and_b32_e32 v207, 0xffff0000, v184
	v_pk_fma_f32 v[8:9], v[8:9], v[204:205], v[206:207]
	v_lshlrev_b32_e32 v204, 16, v181
	v_and_b32_e32 v205, 0xffff0000, v181
	v_lshlrev_b32_e32 v206, 16, v185
	v_and_b32_e32 v207, 0xffff0000, v185
	v_pk_fma_f32 v[10:11], v[10:11], v[204:205], v[206:207]
	v_cvt_pk_bf16_f32 v12, v12, v13
	v_cvt_pk_bf16_f32 v13, v14, v15
	v_cvt_pk_bf16_f32 v14, v8, v9
	v_cvt_pk_bf16_f32 v15, v10, v11
	v_add_u32_e32 v212, 0xb0000, v209
	global_store_dwordx4 v212, v[12:15], s[6:7]
	s_waitcnt vmcnt(15)
	v_lshlrev_b32_e32 v204, 16, v186
	v_and_b32_e32 v205, 0xffff0000, v186
	v_lshlrev_b32_e32 v206, 16, v190
	v_and_b32_e32 v207, 0xffff0000, v190
	v_pk_fma_f32 v[4:5], v[4:5], v[204:205], v[206:207]
	v_lshlrev_b32_e32 v204, 16, v187
	v_and_b32_e32 v205, 0xffff0000, v187
	v_lshlrev_b32_e32 v206, 16, v191
	v_and_b32_e32 v207, 0xffff0000, v191
	v_pk_fma_f32 v[6:7], v[6:7], v[204:205], v[206:207]
	v_lshlrev_b32_e32 v204, 16, v188
	v_and_b32_e32 v205, 0xffff0000, v188
	v_lshlrev_b32_e32 v206, 16, v192
	v_and_b32_e32 v207, 0xffff0000, v192
	v_pk_fma_f32 v[0:1], v[0:1], v[204:205], v[206:207]
	v_lshlrev_b32_e32 v204, 16, v189
	v_and_b32_e32 v205, 0xffff0000, v189
	v_lshlrev_b32_e32 v206, 16, v193
	v_and_b32_e32 v207, 0xffff0000, v193
	v_pk_fma_f32 v[2:3], v[2:3], v[204:205], v[206:207]
	v_cvt_pk_bf16_f32 v4, v4, v5
	v_cvt_pk_bf16_f32 v5, v6, v7
	v_cvt_pk_bf16_f32 v6, v0, v1
	v_cvt_pk_bf16_f32 v7, v2, v3
	global_store_dwordx4 v212, v[4:7], s[6:7] offset:256
	s_and_b64 vcc, exec, s[2:3]
	s_mov_b32 s45, s12
	s_mov_b64 s[20:21], s[16:17]
	s_mov_b64 s[18:19], s[14:15]
	s_mov_b32 s1, s44
	s_cbranch_vccz .LBB0_994
	s_waitcnt vmcnt(0)
	s_cmpk_gt_u32 s27, 0xff
	s_cbranch_scc1 .LBB0_1007
	s_barrier

; #define PG8_STAGE(bufoff, gbase, voff) do { _Pragma("unroll") for (int _i = 0; _i < 2; ++_i) \
;     __builtin_amdgcn_global_load_lds((const unsigned*)((const char*)(gbase) + (voff)[_i]), (LAS unsigned*)(lds + (bufoff) + ldsw + _i * 8192), 16, 0, 0); } while (0)
; #define PG8_LDA(dst, b, h) do { _Pragma("unroll") for (int m = 0; m < 4; ++m) _Pragma("unroll") for (int k = 0; k < 2; ++k) dst[m][k] = *(const LAS bf16x8*)(lds + PG8_SA(b, h) + aoff + m * 2048 + k * 1024); } while (0)
; #define PG8_LDB(dst, b, h) do { _Pragma("unroll") for (int n = 0; n < 2; ++n) _Pragma("unroll") for (int k = 0; k < 2; ++k) dst[n][k] = *(const LAS bf16x8*)(lds + PG8_SB(b, h) + boff + n * 2048 + k * 1024); } while (0)
; #define PG8_MMA(ai, bj, At, Bt) do { __builtin_amdgcn_s_setprio(1); _Pragma("unroll") for (int m = 0; m < 4; ++m) _Pragma("unroll") for (int n = 0; n < 2; ++n) _Pragma("unroll") for (int k = 0; k < 2; ++k) \
;     acc[ai][bj][m][n] = __builtin_amdgcn_mfma_f32_16x16x32_bf16(Bt[n][k], At[m][k], acc[ai][bj][m][n], 0, 0, 0); __builtin_amdgcn_s_setprio(0); } while (0)
; template <class Epi>
; __device__ __forceinline__ void gemm_phase(LAS unsigned char* lds, const Gemm g, const StaticOrder& S, const Epi& E, int wv0) {
;     ...
;       PG8_LDB(B0, 0, 0); PG8_SCHED; PG8_LDA(At, 0, 0); PG8_STAGE(PG8_SA(1, 1), a1 + hstepA, voffA);
;       PG8_WAIT_L(8); PG8_BAR; PG8_WAIT_L(0); PG8_MMA(0, 0, At, B0); PG8_BAR; PG8_SCHED;
;       PG8_LDB(B1, 0, 1); PG8_STAGE(PG8_SB(0, 0), b2, voffB);
;       PG8_BAR; PG8_WAIT_L(0); PG8_MMA(0, 1, At, B1); PG8_BAR;
;       PG8_LDA(At, 0, 1); PG8_STAGE(PG8_SA(0, 0), a2, voffA);
;       PG8_BAR; PG8_WAIT_L(0); PG8_MMA(1, 0, At, B0); PG8_BAR; PG8_SCHED;
;       PG8_STAGE(PG8_SB(0, 1), b2 + hstepB, voffB);
;       PG8_WAIT_V(6); PG8_BAR; PG8_MMA(1, 1, At, B1); PG8_BAR;
;       PG8_LDB(B0, 1, 0); PG8_SCHED; PG8_LDA(At, 1, 0); PG8_STAGE(PG8_SA(0, 1), a2 + hstepA, voffA);
;       PG8_WAIT_L(8); PG8_BAR; PG8_WAIT_L(0); PG8_MMA(0, 0, At, B0); PG8_BAR; PG8_SCHED;
;       PG8_LDB(B1, 1, 1); PG8_STAGE(PG8_SB(1, 0), b3, voffB);
;       PG8_BAR; PG8_WAIT_L(0); PG8_MMA(0, 1, At, B1); PG8_BAR;
;       PG8_LDA(At, 1, 1); PG8_STAGE(PG8_SA(1, 0), a3, voffA);
;       PG8_BAR; PG8_WAIT_L(0); PG8_MMA(1, 0, At, B0); PG8_BAR; PG8_SCHED;
;       PG8_STAGE(PG8_SB(1, 1), b3 + hstepB, voffB);
;       PG8_WAIT_V(6); PG8_BAR; PG8_MMA(1, 1, At, B1); PG8_BAR;
.LBB0_1025:
	s_add_u32 s4, s20, 0x100
	s_addc_u32 s5, s21, 0
	s_add_i32 s0, 0, 0x10000
	v_add_u32_e32 v142, s0, v211
	ds_read_b128 v[130:133], v142
	ds_read_b128 v[134:137], v142 offset:1024
	ds_read_b128 v[138:141], v142 offset:2048
	ds_read_b128 v[142:145], v142 offset:3072
	s_cmp_eq_u32 s51, 12
	s_cselect_b32 s25, s17, s5
	s_cselect_b32 s24, s16, s4
	s_cselect_b32 s23, s15, s50
	s_cselect_b32 s22, s48, s49
	v_lshl_add_u64 v[178:179], s[20:21], 0, v[192:193]
	s_add_i32 m0, s38, 0xc000
	ds_read_b128 v[146:149], v213
	ds_read_b128 v[150:153], v213 offset:1024
	ds_read_b128 v[154:157], v213 offset:2048
	ds_read_b128 v[158:161], v213 offset:3072
	ds_read_b128 v[162:165], v213 offset:4096
	ds_read_b128 v[166:169], v213 offset:5120
	ds_read_b128 v[170:173], v213 offset:6144
	ds_read_b128 v[174:177], v213 offset:7168
	global_load_lds_dwordx4 v[178:179], off
	v_lshl_add_u64 v[178:179], s[20:21], 0, v[194:195]
	s_add_i32 m0, s38, 0xe000
	s_nop 0
	global_load_lds_dwordx4 v[178:179], off
	s_waitcnt lgkmcnt(8)
	s_barrier
	s_waitcnt lgkmcnt(0)
	s_setprio 1
	s_waitcnt lgkmcnt(0)
	v_mfma_f32_16x16x32_bf16 v[126:129], v[130:133], v[146:149], v[126:129]
	v_mfma_f32_16x16x32_bf16 v[122:125], v[138:141], v[146:149], v[122:125]
	v_mfma_f32_16x16x32_bf16 v[110:113], v[130:133], v[154:157], v[110:113]
	v_mfma_f32_16x16x32_bf16 v[106:109], v[138:141], v[154:157], v[106:109]
	v_mfma_f32_16x16x32_bf16 v[92:95], v[130:133], v[162:165], v[92:95]
	v_mfma_f32_16x16x32_bf16 v[88:91], v[138:141], v[162:165], v[88:91]
	v_mfma_f32_16x16x32_bf16 v[76:79], v[130:133], v[170:173], v[76:79]
	v_mfma_f32_16x16x32_bf16 v[72:75], v[138:141], v[170:173], v[72:75]
	v_mfma_f32_16x16x32_bf16 v[126:129], v[134:137], v[150:153], v[126:129]
	v_mfma_f32_16x16x32_bf16 v[122:125], v[142:145], v[150:153], v[122:125]
	v_mfma_f32_16x16x32_bf16 v[110:113], v[134:137], v[158:161], v[110:113]
	v_mfma_f32_16x16x32_bf16 v[106:109], v[142:145], v[158:161], v[106:109]
	v_mfma_f32_16x16x32_bf16 v[92:95], v[134:137], v[166:169], v[92:95]
	v_mfma_f32_16x16x32_bf16 v[88:91], v[142:145], v[166:169], v[88:91]
	v_mfma_f32_16x16x32_bf16 v[76:79], v[134:137], v[174:177], v[76:79]
	v_mfma_f32_16x16x32_bf16 v[72:75], v[142:145], v[174:177], v[72:75]
	s_setprio 0
	s_barrier
	s_add_i32 s52, 0, 0x14000
	s_add_i32 s0, s0, s37
	v_add_u32_e32 v200, s52, v211
	v_lshl_add_u64 v[204:205], s[22:23], 0, v[96:97]
	s_mov_b32 m0, s0
	ds_read_b128 v[178:181], v200
	ds_read_b128 v[182:185], v200 offset:1024
	ds_read_b128 v[196:199], v200 offset:2048
	ds_read_b128 v[200:203], v200 offset:3072
	global_load_lds_dwordx4 v[204:205], off
	v_lshl_add_u64 v[206:207], s[22:23], 0, v[190:191]
	s_add_i32 m0, s0, 0x2000
	s_nop 0
	global_load_lds_dwordx4 v[206:207], off
	s_barrier
	s_waitcnt lgkmcnt(0)
	s_setprio 1
	s_waitcnt lgkmcnt(0)
	v_mfma_f32_16x16x32_bf16 v[118:121], v[178:181], v[146:149], v[118:121]
	v_mfma_f32_16x16x32_bf16 v[114:117], v[196:199], v[146:149], v[114:117]
	v_mfma_f32_16x16x32_bf16 v[102:105], v[178:181], v[154:157], v[102:105]
	v_mfma_f32_16x16x32_bf16 v[98:101], v[196:199], v[154:157], v[98:101]
	v_mfma_f32_16x16x32_bf16 v[84:87], v[178:181], v[162:165], v[84:87]
	v_mfma_f32_16x16x32_bf16 v[80:83], v[196:199], v[162:165], v[80:83]
	v_mfma_f32_16x16x32_bf16 v[68:71], v[178:181], v[170:173], v[68:71]
	v_mfma_f32_16x16x32_bf16 v[64:67], v[196:199], v[170:173], v[64:67]
	v_mfma_f32_16x16x32_bf16 v[118:121], v[182:185], v[150:153], v[118:121]
	v_mfma_f32_16x16x32_bf16 v[114:117], v[200:203], v[150:153], v[114:117]
	v_mfma_f32_16x16x32_bf16 v[102:105], v[182:185], v[158:161], v[102:105]
	v_mfma_f32_16x16x32_bf16 v[98:101], v[200:203], v[158:161], v[98:101]
	v_mfma_f32_16x16x32_bf16 v[84:87], v[182:185], v[166:169], v[84:87]
	v_mfma_f32_16x16x32_bf16 v[80:83], v[200:203], v[166:169], v[80:83]
	v_mfma_f32_16x16x32_bf16 v[68:71], v[182:185], v[174:177], v[68:71]
	v_mfma_f32_16x16x32_bf16 v[64:67], v[200:203], v[174:177], v[64:67]
	s_setprio 0
	s_mov_b32 m0, s38
	v_lshl_add_u64 v[208:209], s[24:25], 0, v[186:187]
	s_barrier
	ds_read_b128 v[146:149], v213 offset:16384
	ds_read_b128 v[150:153], v213 offset:17408
	ds_read_b128 v[154:157], v213 offset:18432
	ds_read_b128 v[158:161], v213 offset:19456
	ds_read_b128 v[162:165], v213 offset:20480
	ds_read_b128 v[166:169], v213 offset:21504
	ds_read_b128 v[170:173], v213 offset:22528
	ds_read_b128 v[174:177], v213 offset:23552
	global_load_lds_dwordx4 v[208:209], off
	v_lshl_add_u64 v[214:215], s[24:25], 0, v[188:189]
	s_mov_b32 m0, s39
	s_nop 0
	global_load_lds_dwordx4 v[214:215], off
	s_barrier
	s_waitcnt lgkmcnt(0)
	s_setprio 1
	s_waitcnt lgkmcnt(0)
	v_mfma_f32_16x16x32_bf16 v[60:63], v[130:133], v[146:149], v[60:63]
	v_mfma_f32_16x16x32_bf16 v[56:59], v[138:141], v[146:149], v[56:59]
	v_mfma_f32_16x16x32_bf16 v[44:47], v[130:133], v[154:157], v[44:47]
	v_mfma_f32_16x16x32_bf16 v[40:43], v[138:141], v[154:157], v[40:43]
	v_mfma_f32_16x16x32_bf16 v[28:31], v[130:133], v[162:165], v[28:31]
	v_mfma_f32_16x16x32_bf16 v[24:27], v[138:141], v[162:165], v[24:27]
	v_mfma_f32_16x16x32_bf16 v[12:15], v[130:133], v[170:173], v[12:15]
	v_mfma_f32_16x16x32_bf16 v[8:11], v[138:141], v[170:173], v[8:11]
	v_mfma_f32_16x16x32_bf16 v[60:63], v[134:137], v[150:153], v[60:63]
	v_mfma_f32_16x16x32_bf16 v[56:59], v[142:145], v[150:153], v[56:59]
	v_mfma_f32_16x16x32_bf16 v[44:47], v[134:137], v[158:161], v[44:47]
	v_mfma_f32_16x16x32_bf16 v[40:43], v[142:145], v[158:161], v[40:43]
	v_mfma_f32_16x16x32_bf16 v[28:31], v[134:137], v[166:169], v[28:31]
	v_mfma_f32_16x16x32_bf16 v[24:27], v[142:145], v[166:169], v[24:27]
	v_mfma_f32_16x16x32_bf16 v[12:15], v[134:137], v[174:177], v[12:15]
	v_mfma_f32_16x16x32_bf16 v[8:11], v[142:145], v[174:177], v[8:11]
	s_setprio 0
	s_barrier
; #define PG8_STAGE(bufoff, gbase, voff) do { _Pragma("unroll") for (int _i = 0; _i < 2; ++_i) \
;     __builtin_amdgcn_global_load_lds((const unsigned*)((const char*)(gbase) + (voff)[_i]), (LAS unsigned*)(lds + (bufoff) + ldsw + _i * 8192), 16, 0, 0); } while (0)
; #define PG8_LDA(dst, b, h) do { _Pragma("unroll") for (int m = 0; m < 4; ++m) _Pragma("unroll") for (int k = 0; k < 2; ++k) dst[m][k] = *(const LAS bf16x8*)(lds + PG8_SA(b, h) + aoff + m * 2048 + k * 1024); } while (0)
; #define PG8_LDB(dst, b, h) do { _Pragma("unroll") for (int n = 0; n < 2; ++n) _Pragma("unroll") for (int k = 0; k < 2; ++k) dst[n][k] = *(const LAS bf16x8*)(lds + PG8_SB(b, h) + boff + n * 2048 + k * 1024); } while (0)
; #define PG8_MMA(ai, bj, At, Bt) do { __builtin_amdgcn_s_setprio(1); _Pragma("unroll") for (int m = 0; m < 4; ++m) _Pragma("unroll") for (int n = 0; n < 2; ++n) _Pragma("unroll") for (int k = 0; k < 2; ++k) \
;     acc[ai][bj][m][n] = __builtin_amdgcn_mfma_f32_16x16x32_bf16(Bt[n][k], At[m][k], acc[ai][bj][m][n], 0, 0, 0); __builtin_amdgcn_s_setprio(0); } while (0)
; template <class Epi>
; __device__ __forceinline__ void gemm_phase(LAS unsigned char* lds, const Gemm g, const StaticOrder& S, const Epi& E, int wv0) {
;     ...
;       PG8_LDB(B0, 0, 0); PG8_SCHED; PG8_LDA(At, 0, 0); PG8_STAGE(PG8_SA(1, 1), a1 + hstepA, voffA);
;       PG8_WAIT_L(8); PG8_BAR; PG8_WAIT_L(0); PG8_MMA(0, 0, At, B0); PG8_BAR; PG8_SCHED;
;       PG8_LDB(B1, 0, 1); PG8_STAGE(PG8_SB(0, 0), b2, voffB);
;       PG8_BAR; PG8_WAIT_L(0); PG8_MMA(0, 1, At, B1); PG8_BAR;
;       PG8_LDA(At, 0, 1); PG8_STAGE(PG8_SA(0, 0), a2, voffA);
;       PG8_BAR; PG8_WAIT_L(0); PG8_MMA(1, 0, At, B0); PG8_BAR; PG8_SCHED;
;       PG8_STAGE(PG8_SB(0, 1), b2 + hstepB, voffB);
;       PG8_WAIT_V(6); PG8_BAR; PG8_MMA(1, 1, At, B1); PG8_BAR;
;       PG8_LDB(B0, 1, 0); PG8_SCHED; PG8_LDA(At, 1, 0); PG8_STAGE(PG8_SA(0, 1), a2 + hstepA, voffA);
;       PG8_WAIT_L(8); PG8_BAR; PG8_WAIT_L(0); PG8_MMA(0, 0, At, B0); PG8_BAR; PG8_SCHED;
;       PG8_LDB(B1, 1, 1); PG8_STAGE(PG8_SB(1, 0), b3, voffB);
;       PG8_BAR; PG8_WAIT_L(0); PG8_MMA(0, 1, At, B1); PG8_BAR;
;       PG8_LDA(At, 1, 1); PG8_STAGE(PG8_SA(1, 0), a3, voffA);
;       PG8_BAR; PG8_WAIT_L(0); PG8_MMA(1, 0, At, B0); PG8_BAR; PG8_SCHED;
;       PG8_STAGE(PG8_SB(1, 1), b3 + hstepB, voffB);
;       PG8_WAIT_V(6); PG8_BAR; PG8_MMA(1, 1, At, B1); PG8_BAR;
	s_add_u32 s20, s22, 0x40000
	s_addc_u32 s21, s23, 0
	s_add_i32 s0, s52, s37
	v_lshl_add_u64 v[130:131], s[20:21], 0, v[96:97]
	s_mov_b32 m0, s0
	s_nop 0
	global_load_lds_dwordx4 v[130:131], off
	v_lshl_add_u64 v[130:131], s[20:21], 0, v[190:191]
	s_add_i32 m0, s0, 0x2000
	s_nop 0
	global_load_lds_dwordx4 v[130:131], off
	s_waitcnt vmcnt(6)
	s_barrier
	s_setprio 1
	v_mfma_f32_16x16x32_bf16 v[52:55], v[178:181], v[146:149], v[52:55]
	v_mfma_f32_16x16x32_bf16 v[48:51], v[196:199], v[146:149], v[48:51]
	v_mfma_f32_16x16x32_bf16 v[36:39], v[178:181], v[154:157], v[36:39]
	v_mfma_f32_16x16x32_bf16 v[32:35], v[196:199], v[154:157], v[32:35]
	v_mfma_f32_16x16x32_bf16 v[20:23], v[178:181], v[162:165], v[20:23]
	v_mfma_f32_16x16x32_bf16 v[16:19], v[196:199], v[162:165], v[16:19]
	v_mfma_f32_16x16x32_bf16 v[4:7], v[178:181], v[170:173], v[4:7]
	v_mfma_f32_16x16x32_bf16 v[0:3], v[196:199], v[170:173], v[0:3]
	v_mfma_f32_16x16x32_bf16 v[52:55], v[182:185], v[150:153], v[52:55]
	v_mfma_f32_16x16x32_bf16 v[48:51], v[200:203], v[150:153], v[48:51]
	v_mfma_f32_16x16x32_bf16 v[36:39], v[182:185], v[158:161], v[36:39]
	v_mfma_f32_16x16x32_bf16 v[32:35], v[200:203], v[158:161], v[32:35]
	v_mfma_f32_16x16x32_bf16 v[20:23], v[182:185], v[166:169], v[20:23]
	v_mfma_f32_16x16x32_bf16 v[16:19], v[200:203], v[166:169], v[16:19]
	v_mfma_f32_16x16x32_bf16 v[4:7], v[182:185], v[174:177], v[4:7]
	v_mfma_f32_16x16x32_bf16 v[0:3], v[200:203], v[174:177], v[0:3]
	s_setprio 0
	s_add_i32 s0, 0, 0x18000
	v_add_u32_e32 v142, s0, v211
	s_barrier
	ds_read_b128 v[130:133], v142
	ds_read_b128 v[134:137], v142 offset:1024
	ds_read_b128 v[138:141], v142 offset:2048
	ds_read_b128 v[142:145], v142 offset:3072
	s_add_u32 s20, s24, 0x114000
	s_addc_u32 s21, s25, 0
	s_mov_b32 m0, s40
	v_lshl_add_u64 v[178:179], s[20:21], 0, v[186:187]
	ds_read_b128 v[146:149], v213 offset:32768
	ds_read_b128 v[150:153], v213 offset:33792
	ds_read_b128 v[154:157], v213 offset:34816
	ds_read_b128 v[158:161], v213 offset:35840
	ds_read_b128 v[162:165], v213 offset:36864
	ds_read_b128 v[166:169], v213 offset:37888
	ds_read_b128 v[170:173], v213 offset:38912
	ds_read_b128 v[174:177], v213 offset:39936
	global_load_lds_dwordx4 v[178:179], off
	v_lshl_add_u64 v[178:179], s[20:21], 0, v[188:189]
	s_mov_b32 m0, s41
	s_nop 0
	global_load_lds_dwordx4 v[178:179], off
	s_waitcnt lgkmcnt(8)
	s_barrier
	s_waitcnt lgkmcnt(0)
	s_setprio 1
	s_waitcnt lgkmcnt(0)
	v_mfma_f32_16x16x32_bf16 v[126:129], v[130:133], v[146:149], v[126:129]
	v_mfma_f32_16x16x32_bf16 v[122:125], v[138:141], v[146:149], v[122:125]
	v_mfma_f32_16x16x32_bf16 v[110:113], v[130:133], v[154:157], v[110:113]
	v_mfma_f32_16x16x32_bf16 v[106:109], v[138:141], v[154:157], v[106:109]
	v_mfma_f32_16x16x32_bf16 v[92:95], v[130:133], v[162:165], v[92:95]
	v_mfma_f32_16x16x32_bf16 v[88:91], v[138:141], v[162:165], v[88:91]
	v_mfma_f32_16x16x32_bf16 v[76:79], v[130:133], v[170:173], v[76:79]
	v_mfma_f32_16x16x32_bf16 v[72:75], v[138:141], v[170:173], v[72:75]
	v_mfma_f32_16x16x32_bf16 v[126:129], v[134:137], v[150:153], v[126:129]
	v_mfma_f32_16x16x32_bf16 v[122:125], v[142:145], v[150:153], v[122:125]
	v_mfma_f32_16x16x32_bf16 v[110:113], v[134:137], v[158:161], v[110:113]
	v_mfma_f32_16x16x32_bf16 v[106:109], v[142:145], v[158:161], v[106:109]
	v_mfma_f32_16x16x32_bf16 v[92:95], v[134:137], v[166:169], v[92:95]
	v_mfma_f32_16x16x32_bf16 v[88:91], v[142:145], v[166:169], v[88:91]
	v_mfma_f32_16x16x32_bf16 v[76:79], v[134:137], v[174:177], v[76:79]
	v_mfma_f32_16x16x32_bf16 v[72:75], v[142:145], v[174:177], v[72:75]
	s_setprio 0
	s_barrier
	s_add_i32 s24, 0, 0x1c000
	s_add_i32 s0, s0, s37
	v_add_u32_e32 v200, s24, v211
	v_lshl_add_u64 v[204:205], v[204:205], 0, s[72:73]
	s_mov_b32 m0, s0
	ds_read_b128 v[178:181], v200
	ds_read_b128 v[182:185], v200 offset:1024
	ds_read_b128 v[196:199], v200 offset:2048
	ds_read_b128 v[200:203], v200 offset:3072
	global_load_lds_dwordx4 v[204:205], off
	v_lshl_add_u64 v[204:205], v[206:207], 0, s[72:73]
	s_add_i32 m0, s0, 0x2000
	s_nop 0
	global_load_lds_dwordx4 v[204:205], off
	s_barrier
	s_waitcnt lgkmcnt(0)
	s_setprio 1
	s_waitcnt lgkmcnt(0)
	v_mfma_f32_16x16x32_bf16 v[118:121], v[178:181], v[146:149], v[118:121]
	v_mfma_f32_16x16x32_bf16 v[114:117], v[196:199], v[146:149], v[114:117]
	v_mfma_f32_16x16x32_bf16 v[102:105], v[178:181], v[154:157], v[102:105]
	v_mfma_f32_16x16x32_bf16 v[98:101], v[196:199], v[154:157], v[98:101]
	v_mfma_f32_16x16x32_bf16 v[84:87], v[178:181], v[162:165], v[84:87]
	v_mfma_f32_16x16x32_bf16 v[80:83], v[196:199], v[162:165], v[80:83]
	v_mfma_f32_16x16x32_bf16 v[68:71], v[178:181], v[170:173], v[68:71]
	v_mfma_f32_16x16x32_bf16 v[64:67], v[196:199], v[170:173], v[64:67]
	v_mfma_f32_16x16x32_bf16 v[118:121], v[182:185], v[150:153], v[118:121]
	v_mfma_f32_16x16x32_bf16 v[114:117], v[200:203], v[150:153], v[114:117]
	v_mfma_f32_16x16x32_bf16 v[102:105], v[182:185], v[158:161], v[102:105]
	v_mfma_f32_16x16x32_bf16 v[98:101], v[200:203], v[158:161], v[98:101]
	v_mfma_f32_16x16x32_bf16 v[84:87], v[182:185], v[166:169], v[84:87]
	v_mfma_f32_16x16x32_bf16 v[80:83], v[200:203], v[166:169], v[80:83]
	v_mfma_f32_16x16x32_bf16 v[68:71], v[182:185], v[174:177], v[68:71]
	v_mfma_f32_16x16x32_bf16 v[64:67], v[200:203], v[174:177], v[64:67]
	s_setprio 0
	s_mov_b32 m0, s42
	v_lshl_add_u64 v[204:205], v[208:209], 0, s[72:73]
	s_barrier
	ds_read_b128 v[146:149], v213 offset:49152
	ds_read_b128 v[150:153], v213 offset:50176
	ds_read_b128 v[154:157], v213 offset:51200
	ds_read_b128 v[158:161], v213 offset:52224
	ds_read_b128 v[162:165], v213 offset:53248
	ds_read_b128 v[166:169], v213 offset:54272
	ds_read_b128 v[170:173], v213 offset:55296
	ds_read_b128 v[174:177], v213 offset:56320
	global_load_lds_dwordx4 v[204:205], off
	v_lshl_add_u64 v[204:205], v[214:215], 0, s[72:73]
	s_mov_b32 m0, s43
	s_nop 0
	global_load_lds_dwordx4 v[204:205], off
	s_barrier
; __device__ __forceinline__ float bf_lo(unsigned u) { return __uint_as_float(u << 16); }
; __device__ __forceinline__ float bf_hi(unsigned u) { return __uint_as_float(u & 0xffff0000u); }
; #define PG8_STAGE(bufoff, gbase, voff) do { _Pragma("unroll") for (int _i = 0; _i < 2; ++_i) \
;     __builtin_amdgcn_global_load_lds((const unsigned*)((const char*)(gbase) + (voff)[_i]), (LAS unsigned*)(lds + (bufoff) + ldsw + _i * 8192), 16, 0, 0); } while (0)
; template <class Epi>
; __device__ __forceinline__ void gemm_phase(LAS unsigned char* lds, const Gemm g, const StaticOrder& S, const Epi& E, int wv0) {
;     ...
;       PG8_WAIT_V(6); PG8_BAR; PG8_MMA(1, 1, At, B1); PG8_BAR;
;       PG8_LDB(B0, 1, 0); PG8_SCHED; PG8_LDA(At, 1, 0); PG8_STAGE(PG8_SA(0, 1), a2 + hstepA, voffA);
;       PG8_WAIT_L(8); PG8_BAR; PG8_WAIT_L(0); PG8_MMA(0, 0, At, B0); PG8_BAR; PG8_SCHED;
;       PG8_LDB(B1, 1, 1); PG8_STAGE(PG8_SB(1, 0), b3, voffB);
;       PG8_BAR; PG8_WAIT_L(0); PG8_MMA(0, 1, At, B1); PG8_BAR;
;       PG8_LDA(At, 1, 1); PG8_STAGE(PG8_SA(1, 0), a3, voffA);
;       PG8_BAR; PG8_WAIT_L(0); PG8_MMA(1, 0, At, B0); PG8_BAR; PG8_SCHED;
;       PG8_STAGE(PG8_SB(1, 1), b3 + hstepB, voffB);
;       PG8_WAIT_V(6); PG8_BAR; PG8_MMA(1, 1, At, B1); PG8_BAR;
;   __device__ __forceinline__ void preload(EpiPre& q, int row, int col) const {
;     ...
;     } else if (MODE == E_PROJ) {
;       q.u0 = *(const u32x4*)(e.b0 + (size_t)row * NG + e.aux * DM + col);
;       if (e.aux > 0) q.u1 = *(const u32x4*)((const bf16_t*)e.facc + (size_t)row * DM + col);
;   __device__ __forceinline__ void emit(const EpiPre& q0, int row, int col, f32x4 a, f32x4 b, const f32x4 (&hb)[2][2], const float (&hs)[2][4], int ai_, int m_, int bj_) const {
;     ...
;     } else if (MODE == E_PROJ) {
;       const int br = e.aux; const u32x4 gw = q.u0;
;       v[0] *= bf_lo(gw.x); v[1] *= bf_hi(gw.x); v[2] *= bf_lo(gw.y); v[3] *= bf_hi(gw.y);
;       v[4] *= bf_lo(gw.z); v[5] *= bf_hi(gw.z); v[6] *= bf_lo(gw.w); v[7] *= bf_hi(gw.w);
;       bf16_t* fa = (bf16_t*)e.facc + (size_t)row * DM + col;
;       if (br > 0) { const u32x4 pw = q.u1;
;         v[0] += bf_lo(pw.x); v[1] += bf_hi(pw.x); v[2] += bf_lo(pw.y); v[3] += bf_hi(pw.y); v[4] += bf_lo(pw.z); v[5] += bf_hi(pw.z); v[6] += bf_lo(pw.w); v[7] += bf_hi(pw.w); }
;       if (br == 2) store8bf((bf16_t*)e.out + (size_t)row * DM + col, v);
;       else store8bf(fa, v);
	s_waitcnt lgkmcnt(0)
	s_setprio 1
	s_waitcnt lgkmcnt(0)
	v_mfma_f32_16x16x32_bf16 v[60:63], v[130:133], v[146:149], v[60:63]
	v_mfma_f32_16x16x32_bf16 v[56:59], v[138:141], v[146:149], v[56:59]
	v_mfma_f32_16x16x32_bf16 v[44:47], v[130:133], v[154:157], v[44:47]
	v_mfma_f32_16x16x32_bf16 v[40:43], v[138:141], v[154:157], v[40:43]
	v_mfma_f32_16x16x32_bf16 v[28:31], v[130:133], v[162:165], v[28:31]
	v_mfma_f32_16x16x32_bf16 v[24:27], v[138:141], v[162:165], v[24:27]
	v_mfma_f32_16x16x32_bf16 v[12:15], v[130:133], v[170:173], v[12:15]
	v_mfma_f32_16x16x32_bf16 v[8:11], v[138:141], v[170:173], v[8:11]
	v_mfma_f32_16x16x32_bf16 v[60:63], v[134:137], v[150:153], v[60:63]
	v_mfma_f32_16x16x32_bf16 v[56:59], v[142:145], v[150:153], v[56:59]
	v_mfma_f32_16x16x32_bf16 v[44:47], v[134:137], v[158:161], v[44:47]
	v_mfma_f32_16x16x32_bf16 v[40:43], v[142:145], v[158:161], v[40:43]
	v_mfma_f32_16x16x32_bf16 v[28:31], v[134:137], v[166:169], v[28:31]
	v_mfma_f32_16x16x32_bf16 v[24:27], v[142:145], v[166:169], v[24:27]
	v_mfma_f32_16x16x32_bf16 v[12:15], v[134:137], v[174:177], v[12:15]
	v_mfma_f32_16x16x32_bf16 v[8:11], v[142:145], v[174:177], v[8:11]
	s_setprio 0
	s_barrier
	s_add_u32 s20, s22, 0x40080
	s_addc_u32 s21, s23, 0
	s_add_i32 s0, s24, s37
	v_lshl_add_u64 v[130:131], s[20:21], 0, v[96:97]
	s_mov_b32 m0, s0
	s_nop 0
	global_load_lds_dwordx4 v[130:131], off
	v_lshl_add_u64 v[130:131], s[20:21], 0, v[190:191]
	s_add_i32 m0, s0, 0x2000
	s_nop 0
	global_load_lds_dwordx4 v[130:131], off
	s_waitcnt vmcnt(6)
	s_barrier
	s_setprio 1
	v_mfma_f32_16x16x32_bf16 v[52:55], v[178:181], v[146:149], v[52:55]
	v_mfma_f32_16x16x32_bf16 v[48:51], v[196:199], v[146:149], v[48:51]
	v_mfma_f32_16x16x32_bf16 v[36:39], v[178:181], v[154:157], v[36:39]
	v_mfma_f32_16x16x32_bf16 v[32:35], v[196:199], v[154:157], v[32:35]
	v_mfma_f32_16x16x32_bf16 v[20:23], v[178:181], v[162:165], v[20:23]
	v_mfma_f32_16x16x32_bf16 v[16:19], v[196:199], v[162:165], v[16:19]
	v_mfma_f32_16x16x32_bf16 v[4:7], v[178:181], v[170:173], v[4:7]
	v_mfma_f32_16x16x32_bf16 v[0:3], v[196:199], v[170:173], v[0:3]
	v_mfma_f32_16x16x32_bf16 v[52:55], v[182:185], v[150:153], v[52:55]
	v_mfma_f32_16x16x32_bf16 v[48:51], v[200:203], v[150:153], v[48:51]
	v_mfma_f32_16x16x32_bf16 v[36:39], v[182:185], v[158:161], v[36:39]
	v_mfma_f32_16x16x32_bf16 v[32:35], v[200:203], v[158:161], v[32:35]
	v_mfma_f32_16x16x32_bf16 v[20:23], v[182:185], v[166:169], v[20:23]
	v_mfma_f32_16x16x32_bf16 v[16:19], v[200:203], v[166:169], v[16:19]
	v_mfma_f32_16x16x32_bf16 v[4:7], v[182:185], v[174:177], v[4:7]
	v_mfma_f32_16x16x32_bf16 v[0:3], v[200:203], v[174:177], v[0:3]
	s_setprio 0
	s_add_i32 s51, s51, 2
	s_add_u32 s49, s49, 0x100
	s_addc_u32 s50, s50, 0
	s_cmp_gt_u32 s51, 13
	s_mov_b64 s[20:21], s[4:5]
	s_barrier
	s_cbranch_scc0 .LBB0_1025
	v_lshl_add_u32 v209, s1, 8, v210
	v_lshl_or_b32 v214, s47, 8, v212
	v_mul_u32_u24_e32 v208, 0x3000, v209
	v_lshlrev_b32_e32 v209, 12, v209
	v_lshl_add_u32 v208, v214, 1, v208
	v_lshl_add_u32 v209, v214, 1, v209
	v_add_u32_e32 v214, 0x0, v208
	global_load_dwordx4 v[130:133], v214, s[8:9]
	v_add_u32_e32 v215, 0x0, v209
	global_load_dwordx4 v[134:137], v215, s[6:7]
	global_load_dwordx4 v[138:141], v214, s[8:9] offset:256
	global_load_dwordx4 v[142:145], v215, s[6:7] offset:256
	v_add_u32_e32 v214, 0x30000, v208
	global_load_dwordx4 v[146:149], v214, s[8:9]
	v_add_u32_e32 v215, 0x10000, v209
	global_load_dwordx4 v[150:153], v215, s[6:7]
	global_load_dwordx4 v[154:157], v214, s[8:9] offset:256
	global_load_dwordx4 v[158:161], v215, s[6:7] offset:256
	v_add_u32_e32 v214, 0x60000, v208
	global_load_dwordx4 v[162:165], v214, s[8:9]
	v_add_u32_e32 v215, 0x20000, v209
	global_load_dwordx4 v[166:169], v215, s[6:7]
	global_load_dwordx4 v[170:173], v214, s[8:9] offset:256
	global_load_dwordx4 v[174:177], v215, s[6:7] offset:256
	v_add_u32_e32 v214, 0x90000, v208
	global_load_dwordx4 v[178:181], v214, s[8:9]
	v_add_u32_e32 v215, 0x30000, v209
	global_load_dwordx4 v[182:185], v215, s[6:7]
	global_load_dwordx4 v[196:199], v214, s[8:9] offset:256
	global_load_dwordx4 v[200:203], v215, s[6:7] offset:256
	s_waitcnt vmcnt(14)
	v_lshlrev_b32_e32 v204, 16, v130
	v_and_b32_e32 v205, 0xffff0000, v130
	v_lshlrev_b32_e32 v206, 16, v134
	v_and_b32_e32 v207, 0xffff0000, v134
	v_pk_fma_f32 v[126:127], v[126:127], v[204:205], v[206:207]
	v_lshlrev_b32_e32 v204, 16, v131
	v_and_b32_e32 v205, 0xffff0000, v131
	v_lshlrev_b32_e32 v206, 16, v135
	v_and_b32_e32 v207, 0xffff0000, v135
	v_pk_fma_f32 v[128:129], v[128:129], v[204:205], v[206:207]
	v_lshlrev_b32_e32 v204, 16, v132
	v_and_b32_e32 v205, 0xffff0000, v132
	v_lshlrev_b32_e32 v206, 16, v136
	v_and_b32_e32 v207, 0xffff0000, v136
	v_pk_fma_f32 v[122:123], v[122:123], v[204:205], v[206:207]
	v_lshlrev_b32_e32 v204, 16, v133
	v_and_b32_e32 v205, 0xffff0000, v133
	v_lshlrev_b32_e32 v206, 16, v137
	v_and_b32_e32 v207, 0xffff0000, v137
	v_pk_fma_f32 v[124:125], v[124:125], v[204:205], v[206:207]
	v_cvt_pk_bf16_f32 v126, v126, v127
	v_cvt_pk_bf16_f32 v127, v128, v129
	v_cvt_pk_bf16_f32 v128, v122, v123
	v_cvt_pk_bf16_f32 v129, v124, v125
	v_add_u32_e32 v214, 0x180000, v208
	global_load_dwordx4 v[130:133], v214, s[8:9]
	v_add_u32_e32 v215, 0x80000, v209
	global_load_dwordx4 v[134:137], v215, s[6:7]
	s_waitcnt vmcnt(14)
; __device__ __forceinline__ float bf_lo(unsigned u) { return __uint_as_float(u << 16); }
; __device__ __forceinline__ float bf_hi(unsigned u) { return __uint_as_float(u & 0xffff0000u); }
;   __device__ __forceinline__ void preload(EpiPre& q, int row, int col) const {
;     ...
;     } else if (MODE == E_PROJ) {
;       q.u0 = *(const u32x4*)(e.b0 + (size_t)row * NG + e.aux * DM + col);
;       if (e.aux > 0) q.u1 = *(const u32x4*)((const bf16_t*)e.facc + (size_t)row * DM + col);
;   __device__ __forceinline__ void emit(const EpiPre& q0, int row, int col, f32x4 a, f32x4 b, const f32x4 (&hb)[2][2], const float (&hs)[2][4], int ai_, int m_, int bj_) const {
;     ...
;     } else if (MODE == E_PROJ) {
;       const int br = e.aux; const u32x4 gw = q.u0;
;       v[0] *= bf_lo(gw.x); v[1] *= bf_hi(gw.x); v[2] *= bf_lo(gw.y); v[3] *= bf_hi(gw.y);
;       v[4] *= bf_lo(gw.z); v[5] *= bf_hi(gw.z); v[6] *= bf_lo(gw.w); v[7] *= bf_hi(gw.w);
;       bf16_t* fa = (bf16_t*)e.facc + (size_t)row * DM + col;
;       if (br > 0) { const u32x4 pw = q.u1;
;         v[0] += bf_lo(pw.x); v[1] += bf_hi(pw.x); v[2] += bf_lo(pw.y); v[3] += bf_hi(pw.y); v[4] += bf_lo(pw.z); v[5] += bf_hi(pw.z); v[6] += bf_lo(pw.w); v[7] += bf_hi(pw.w); }
;       if (br == 2) store8bf((bf16_t*)e.out + (size_t)row * DM + col, v);
;       else store8bf(fa, v);
	v_lshlrev_b32_e32 v204, 16, v138
	v_and_b32_e32 v205, 0xffff0000, v138
	v_lshlrev_b32_e32 v206, 16, v142
	v_and_b32_e32 v207, 0xffff0000, v142
	v_pk_fma_f32 v[118:119], v[118:119], v[204:205], v[206:207]
	v_lshlrev_b32_e32 v204, 16, v139
	v_and_b32_e32 v205, 0xffff0000, v139
	v_lshlrev_b32_e32 v206, 16, v143
	v_and_b32_e32 v207, 0xffff0000, v143
	v_pk_fma_f32 v[120:121], v[120:121], v[204:205], v[206:207]
	v_lshlrev_b32_e32 v204, 16, v140
	v_and_b32_e32 v205, 0xffff0000, v140
	v_lshlrev_b32_e32 v206, 16, v144
	v_and_b32_e32 v207, 0xffff0000, v144
	v_pk_fma_f32 v[114:115], v[114:115], v[204:205], v[206:207]
	v_lshlrev_b32_e32 v204, 16, v141
	v_and_b32_e32 v205, 0xffff0000, v141
	v_lshlrev_b32_e32 v206, 16, v145
	v_and_b32_e32 v207, 0xffff0000, v145
	v_pk_fma_f32 v[116:117], v[116:117], v[204:205], v[206:207]
	v_cvt_pk_bf16_f32 v118, v118, v119
	v_cvt_pk_bf16_f32 v119, v120, v121
	v_cvt_pk_bf16_f32 v120, v114, v115
	v_cvt_pk_bf16_f32 v121, v116, v117
	global_load_dwordx4 v[138:141], v214, s[8:9] offset:256
	global_load_dwordx4 v[142:145], v215, s[6:7] offset:256
	s_waitcnt vmcnt(14)
	v_lshlrev_b32_e32 v204, 16, v146
	v_and_b32_e32 v205, 0xffff0000, v146
	v_lshlrev_b32_e32 v206, 16, v150
	v_and_b32_e32 v207, 0xffff0000, v150
	v_pk_fma_f32 v[110:111], v[110:111], v[204:205], v[206:207]
	v_lshlrev_b32_e32 v204, 16, v147
	v_and_b32_e32 v205, 0xffff0000, v147
	v_lshlrev_b32_e32 v206, 16, v151
	v_and_b32_e32 v207, 0xffff0000, v151
	v_pk_fma_f32 v[112:113], v[112:113], v[204:205], v[206:207]
	v_lshlrev_b32_e32 v204, 16, v148
	v_and_b32_e32 v205, 0xffff0000, v148
	v_lshlrev_b32_e32 v206, 16, v152
	v_and_b32_e32 v207, 0xffff0000, v152
	v_pk_fma_f32 v[106:107], v[106:107], v[204:205], v[206:207]
	v_lshlrev_b32_e32 v204, 16, v149
	v_and_b32_e32 v205, 0xffff0000, v149
	v_lshlrev_b32_e32 v206, 16, v153
	v_and_b32_e32 v207, 0xffff0000, v153
	v_pk_fma_f32 v[108:109], v[108:109], v[204:205], v[206:207]
	v_cvt_pk_bf16_f32 v110, v110, v111
	v_cvt_pk_bf16_f32 v111, v112, v113
	v_cvt_pk_bf16_f32 v112, v106, v107
	v_cvt_pk_bf16_f32 v113, v108, v109
	v_add_u32_e32 v214, 0x1b0000, v208
	global_load_dwordx4 v[146:149], v214, s[8:9]
	v_add_u32_e32 v215, 0x90000, v209
	global_load_dwordx4 v[150:153], v215, s[6:7]
	s_waitcnt vmcnt(14)
	v_lshlrev_b32_e32 v204, 16, v154
	v_and_b32_e32 v205, 0xffff0000, v154
	v_lshlrev_b32_e32 v206, 16, v158
	v_and_b32_e32 v207, 0xffff0000, v158
	v_pk_fma_f32 v[102:103], v[102:103], v[204:205], v[206:207]
	v_lshlrev_b32_e32 v204, 16, v155
	v_and_b32_e32 v205, 0xffff0000, v155
	v_lshlrev_b32_e32 v206, 16, v159
	v_and_b32_e32 v207, 0xffff0000, v159
	v_pk_fma_f32 v[104:105], v[104:105], v[204:205], v[206:207]
	v_lshlrev_b32_e32 v204, 16, v156
	v_and_b32_e32 v205, 0xffff0000, v156
	v_lshlrev_b32_e32 v206, 16, v160
	v_and_b32_e32 v207, 0xffff0000, v160
	v_pk_fma_f32 v[98:99], v[98:99], v[204:205], v[206:207]
	v_lshlrev_b32_e32 v204, 16, v157
	v_and_b32_e32 v205, 0xffff0000, v157
	v_lshlrev_b32_e32 v206, 16, v161
	v_and_b32_e32 v207, 0xffff0000, v161
	v_pk_fma_f32 v[100:101], v[100:101], v[204:205], v[206:207]
	v_cvt_pk_bf16_f32 v102, v102, v103
	v_cvt_pk_bf16_f32 v103, v104, v105
	v_cvt_pk_bf16_f32 v104, v98, v99
	v_cvt_pk_bf16_f32 v105, v100, v101
	global_load_dwordx4 v[154:157], v214, s[8:9] offset:256
	global_load_dwordx4 v[158:161], v215, s[6:7] offset:256
	s_waitcnt vmcnt(14)
	v_lshlrev_b32_e32 v204, 16, v162
	v_and_b32_e32 v205, 0xffff0000, v162
	v_lshlrev_b32_e32 v206, 16, v166
	v_and_b32_e32 v207, 0xffff0000, v166
	v_pk_fma_f32 v[92:93], v[92:93], v[204:205], v[206:207]
	v_lshlrev_b32_e32 v204, 16, v163
	v_and_b32_e32 v205, 0xffff0000, v163
	v_lshlrev_b32_e32 v206, 16, v167
	v_and_b32_e32 v207, 0xffff0000, v167
	v_pk_fma_f32 v[94:95], v[94:95], v[204:205], v[206:207]
	v_lshlrev_b32_e32 v204, 16, v164
	v_and_b32_e32 v205, 0xffff0000, v164
	v_lshlrev_b32_e32 v206, 16, v168
	v_and_b32_e32 v207, 0xffff0000, v168
	v_pk_fma_f32 v[88:89], v[88:89], v[204:205], v[206:207]
	v_lshlrev_b32_e32 v204, 16, v165
	v_and_b32_e32 v205, 0xffff0000, v165
	v_lshlrev_b32_e32 v206, 16, v169
	v_and_b32_e32 v207, 0xffff0000, v169
	v_pk_fma_f32 v[90:91], v[90:91], v[204:205], v[206:207]
	v_cvt_pk_bf16_f32 v92, v92, v93
	v_cvt_pk_bf16_f32 v93, v94, v95
	v_cvt_pk_bf16_f32 v94, v88, v89
	v_cvt_pk_bf16_f32 v95, v90, v91
	v_add_u32_e32 v214, 0x1e0000, v208
	global_load_dwordx4 v[162:165], v214, s[8:9]
	v_add_u32_e32 v215, 0xa0000, v209
	global_load_dwordx4 v[166:169], v215, s[6:7]
	s_waitcnt vmcnt(14)
	v_lshlrev_b32_e32 v204, 16, v170
	v_and_b32_e32 v205, 0xffff0000, v170
	v_lshlrev_b32_e32 v206, 16, v174
	v_and_b32_e32 v207, 0xffff0000, v174
	v_pk_fma_f32 v[84:85], v[84:85], v[204:205], v[206:207]
	v_lshlrev_b32_e32 v204, 16, v171
	v_and_b32_e32 v205, 0xffff0000, v171
	v_lshlrev_b32_e32 v206, 16, v175
	v_and_b32_e32 v207, 0xffff0000, v175
	v_pk_fma_f32 v[86:87], v[86:87], v[204:205], v[206:207]
	v_lshlrev_b32_e32 v204, 16, v172
	v_and_b32_e32 v205, 0xffff0000, v172
	v_lshlrev_b32_e32 v206, 16, v176
	v_and_b32_e32 v207, 0xffff0000, v176
	v_pk_fma_f32 v[80:81], v[80:81], v[204:205], v[206:207]
	v_lshlrev_b32_e32 v204, 16, v173
	v_and_b32_e32 v205, 0xffff0000, v173
	v_lshlrev_b32_e32 v206, 16, v177
	v_and_b32_e32 v207, 0xffff0000, v177
	v_pk_fma_f32 v[82:83], v[82:83], v[204:205], v[206:207]
	v_cvt_pk_bf16_f32 v84, v84, v85
	v_cvt_pk_bf16_f32 v85, v86, v87
	v_cvt_pk_bf16_f32 v86, v80, v81
	v_cvt_pk_bf16_f32 v87, v82, v83
	global_load_dwordx4 v[170:173], v214, s[8:9] offset:256
	global_load_dwordx4 v[174:177], v215, s[6:7] offset:256
	s_waitcnt vmcnt(14)
; __device__ __forceinline__ float bf_lo(unsigned u) { return __uint_as_float(u << 16); }
; __device__ __forceinline__ float bf_hi(unsigned u) { return __uint_as_float(u & 0xffff0000u); }
;   __device__ __forceinline__ void emit(const EpiPre& q0, int row, int col, f32x4 a, f32x4 b, const f32x4 (&hb)[2][2], const float (&hs)[2][4], int ai_, int m_, int bj_) const {
;     ...
;     } else if (MODE == E_PROJ) {
;       const int br = e.aux; const u32x4 gw = q.u0;
;       v[0] *= bf_lo(gw.x); v[1] *= bf_hi(gw.x); v[2] *= bf_lo(gw.y); v[3] *= bf_hi(gw.y);
;       v[4] *= bf_lo(gw.z); v[5] *= bf_hi(gw.z); v[6] *= bf_lo(gw.w); v[7] *= bf_hi(gw.w);
;       bf16_t* fa = (bf16_t*)e.facc + (size_t)row * DM + col;
;       if (br > 0) { const u32x4 pw = q.u1;
;         v[0] += bf_lo(pw.x); v[1] += bf_hi(pw.x); v[2] += bf_lo(pw.y); v[3] += bf_hi(pw.y); v[4] += bf_lo(pw.z); v[5] += bf_hi(pw.z); v[6] += bf_lo(pw.w); v[7] += bf_hi(pw.w); }
;       if (br == 2) store8bf((bf16_t*)e.out + (size_t)row * DM + col, v);
;       else store8bf(fa, v);
	v_lshlrev_b32_e32 v204, 16, v178
	v_and_b32_e32 v205, 0xffff0000, v178
	v_lshlrev_b32_e32 v206, 16, v182
	v_and_b32_e32 v207, 0xffff0000, v182
	v_pk_fma_f32 v[76:77], v[76:77], v[204:205], v[206:207]
	v_lshlrev_b32_e32 v204, 16, v179
	v_and_b32_e32 v205, 0xffff0000, v179
	v_lshlrev_b32_e32 v206, 16, v183
	v_and_b32_e32 v207, 0xffff0000, v183
	v_pk_fma_f32 v[78:79], v[78:79], v[204:205], v[206:207]
	v_lshlrev_b32_e32 v204, 16, v180
	v_and_b32_e32 v205, 0xffff0000, v180
	v_lshlrev_b32_e32 v206, 16, v184
	v_and_b32_e32 v207, 0xffff0000, v184
	v_pk_fma_f32 v[72:73], v[72:73], v[204:205], v[206:207]
	v_lshlrev_b32_e32 v204, 16, v181
	v_and_b32_e32 v205, 0xffff0000, v181
	v_lshlrev_b32_e32 v206, 16, v185
	v_and_b32_e32 v207, 0xffff0000, v185
	v_pk_fma_f32 v[74:75], v[74:75], v[204:205], v[206:207]
	v_cvt_pk_bf16_f32 v76, v76, v77
	v_cvt_pk_bf16_f32 v77, v78, v79
	v_cvt_pk_bf16_f32 v78, v72, v73
	v_cvt_pk_bf16_f32 v79, v74, v75
	v_add_u32_e32 v214, 0x210000, v208
	global_load_dwordx4 v[178:181], v214, s[8:9]
	v_add_u32_e32 v215, 0xb0000, v209
	global_load_dwordx4 v[182:185], v215, s[6:7]
	s_waitcnt vmcnt(14)
	v_lshlrev_b32_e32 v204, 16, v196
	v_and_b32_e32 v205, 0xffff0000, v196
	v_lshlrev_b32_e32 v206, 16, v200
	v_and_b32_e32 v207, 0xffff0000, v200
	v_pk_fma_f32 v[68:69], v[68:69], v[204:205], v[206:207]
	v_lshlrev_b32_e32 v204, 16, v197
	v_and_b32_e32 v205, 0xffff0000, v197
	v_lshlrev_b32_e32 v206, 16, v201
	v_and_b32_e32 v207, 0xffff0000, v201
	v_pk_fma_f32 v[70:71], v[70:71], v[204:205], v[206:207]
	v_lshlrev_b32_e32 v204, 16, v198
	v_and_b32_e32 v205, 0xffff0000, v198
	v_lshlrev_b32_e32 v206, 16, v202
	v_and_b32_e32 v207, 0xffff0000, v202
	v_pk_fma_f32 v[64:65], v[64:65], v[204:205], v[206:207]
	v_lshlrev_b32_e32 v204, 16, v199
	v_and_b32_e32 v205, 0xffff0000, v199
	v_lshlrev_b32_e32 v206, 16, v203
	v_and_b32_e32 v207, 0xffff0000, v203
	v_pk_fma_f32 v[66:67], v[66:67], v[204:205], v[206:207]
	v_cvt_pk_bf16_f32 v68, v68, v69
	v_cvt_pk_bf16_f32 v69, v70, v71
	v_cvt_pk_bf16_f32 v70, v64, v65
	v_cvt_pk_bf16_f32 v71, v66, v67
	global_load_dwordx4 v[196:199], v214, s[8:9] offset:256
	global_load_dwordx4 v[200:203], v215, s[6:7] offset:256
	v_add_u32_e32 v215, 0x0, v209
	global_store_dwordx4 v215, v[126:129], s[12:13]
	global_store_dwordx4 v215, v[118:121], s[12:13] offset:256
	v_add_u32_e32 v215, 0x10000, v209
	global_store_dwordx4 v215, v[110:113], s[12:13]
	global_store_dwordx4 v215, v[102:105], s[12:13] offset:256
	v_add_u32_e32 v215, 0x20000, v209
	global_store_dwordx4 v215, v[92:95], s[12:13]
	global_store_dwordx4 v215, v[84:87], s[12:13] offset:256
	v_add_u32_e32 v215, 0x30000, v209
	global_store_dwordx4 v215, v[76:79], s[12:13]
	global_store_dwordx4 v215, v[68:71], s[12:13] offset:256
	s_waitcnt vmcnt(22)
	v_lshlrev_b32_e32 v204, 16, v130
	v_and_b32_e32 v205, 0xffff0000, v130
	v_lshlrev_b32_e32 v206, 16, v134
	v_and_b32_e32 v207, 0xffff0000, v134
	v_pk_fma_f32 v[60:61], v[60:61], v[204:205], v[206:207]
	v_lshlrev_b32_e32 v204, 16, v131
	v_and_b32_e32 v205, 0xffff0000, v131
	v_lshlrev_b32_e32 v206, 16, v135
	v_and_b32_e32 v207, 0xffff0000, v135
	v_pk_fma_f32 v[62:63], v[62:63], v[204:205], v[206:207]
	v_lshlrev_b32_e32 v204, 16, v132
	v_and_b32_e32 v205, 0xffff0000, v132
	v_lshlrev_b32_e32 v206, 16, v136
	v_and_b32_e32 v207, 0xffff0000, v136
	v_pk_fma_f32 v[56:57], v[56:57], v[204:205], v[206:207]
	v_lshlrev_b32_e32 v204, 16, v133
	v_and_b32_e32 v205, 0xffff0000, v133
	v_lshlrev_b32_e32 v206, 16, v137
	v_and_b32_e32 v207, 0xffff0000, v137
	v_pk_fma_f32 v[58:59], v[58:59], v[204:205], v[206:207]
	v_cvt_pk_bf16_f32 v60, v60, v61
	v_cvt_pk_bf16_f32 v61, v62, v63
	v_cvt_pk_bf16_f32 v62, v56, v57
	v_cvt_pk_bf16_f32 v63, v58, v59
	v_add_u32_e32 v215, 0x80000, v209
	global_store_dwordx4 v215, v[60:63], s[12:13]
	s_waitcnt vmcnt(21)
	v_lshlrev_b32_e32 v204, 16, v138
	v_and_b32_e32 v205, 0xffff0000, v138
	v_lshlrev_b32_e32 v206, 16, v142
	v_and_b32_e32 v207, 0xffff0000, v142
	v_pk_fma_f32 v[52:53], v[52:53], v[204:205], v[206:207]
	v_lshlrev_b32_e32 v204, 16, v139
	v_and_b32_e32 v205, 0xffff0000, v139
	v_lshlrev_b32_e32 v206, 16, v143
	v_and_b32_e32 v207, 0xffff0000, v143
	v_pk_fma_f32 v[54:55], v[54:55], v[204:205], v[206:207]
	v_lshlrev_b32_e32 v204, 16, v140
	v_and_b32_e32 v205, 0xffff0000, v140
	v_lshlrev_b32_e32 v206, 16, v144
	v_and_b32_e32 v207, 0xffff0000, v144
	v_pk_fma_f32 v[48:49], v[48:49], v[204:205], v[206:207]
	v_lshlrev_b32_e32 v204, 16, v141
	v_and_b32_e32 v205, 0xffff0000, v141
	v_lshlrev_b32_e32 v206, 16, v145
	v_and_b32_e32 v207, 0xffff0000, v145
	v_pk_fma_f32 v[50:51], v[50:51], v[204:205], v[206:207]
	v_cvt_pk_bf16_f32 v52, v52, v53
	v_cvt_pk_bf16_f32 v53, v54, v55
	v_cvt_pk_bf16_f32 v54, v48, v49
	v_cvt_pk_bf16_f32 v55, v50, v51
	global_store_dwordx4 v215, v[52:55], s[12:13] offset:256
	s_waitcnt vmcnt(20)
	v_lshlrev_b32_e32 v204, 16, v146
	v_and_b32_e32 v205, 0xffff0000, v146
	v_lshlrev_b32_e32 v206, 16, v150
	v_and_b32_e32 v207, 0xffff0000, v150
	v_pk_fma_f32 v[44:45], v[44:45], v[204:205], v[206:207]
	v_lshlrev_b32_e32 v204, 16, v147
	v_and_b32_e32 v205, 0xffff0000, v147
	v_lshlrev_b32_e32 v206, 16, v151
	v_and_b32_e32 v207, 0xffff0000, v151
	v_pk_fma_f32 v[46:47], v[46:47], v[204:205], v[206:207]
	v_lshlrev_b32_e32 v204, 16, v148
	v_and_b32_e32 v205, 0xffff0000, v148
	v_lshlrev_b32_e32 v206, 16, v152
	v_and_b32_e32 v207, 0xffff0000, v152
	v_pk_fma_f32 v[40:41], v[40:41], v[204:205], v[206:207]
	v_lshlrev_b32_e32 v204, 16, v149
	v_and_b32_e32 v205, 0xffff0000, v149
	v_lshlrev_b32_e32 v206, 16, v153
	v_and_b32_e32 v207, 0xffff0000, v153
	v_pk_fma_f32 v[42:43], v[42:43], v[204:205], v[206:207]
	v_cvt_pk_bf16_f32 v44, v44, v45
	v_cvt_pk_bf16_f32 v45, v46, v47
	v_cvt_pk_bf16_f32 v46, v40, v41
	v_cvt_pk_bf16_f32 v47, v42, v43
	v_add_u32_e32 v215, 0x90000, v209
	global_store_dwordx4 v215, v[44:47], s[12:13]
	s_waitcnt vmcnt(19)
; __device__ __forceinline__ float bf_lo(unsigned u) { return __uint_as_float(u << 16); }
; __device__ __forceinline__ float bf_hi(unsigned u) { return __uint_as_float(u & 0xffff0000u); }
; template <class Epi>
; __device__ __forceinline__ void gemm_phase(LAS unsigned char* lds, const Gemm g, const StaticOrder& S, const Epi& E, int wv0) {
;     ...
;     E(acc, cur, wr, wc, fr, fq);
;     if (!has_next) break;
; #pragma unroll
;     for (int a = 0; a < 2; ++a)
; #pragma unroll
;       for (int b = 0; b < 2; ++b)
; #pragma unroll
;         for (int m = 0; m < 4; ++m)
; #pragma unroll
;           for (int n = 0; n < 2; ++n) acc[a][b][m][n] = (f32x4){0.f, 0.f, 0.f, 0.f};
;     cur = nxt; cA = nA; cB = nB; ++ui;
;   }
;   __device__ __forceinline__ void emit(const EpiPre& q0, int row, int col, f32x4 a, f32x4 b, const f32x4 (&hb)[2][2], const float (&hs)[2][4], int ai_, int m_, int bj_) const {
;     ...
;     } else if (MODE == E_PROJ) {
;       const int br = e.aux; const u32x4 gw = q.u0;
;       v[0] *= bf_lo(gw.x); v[1] *= bf_hi(gw.x); v[2] *= bf_lo(gw.y); v[3] *= bf_hi(gw.y);
;       v[4] *= bf_lo(gw.z); v[5] *= bf_hi(gw.z); v[6] *= bf_lo(gw.w); v[7] *= bf_hi(gw.w);
;       bf16_t* fa = (bf16_t*)e.facc + (size_t)row * DM + col;
;       if (br > 0) { const u32x4 pw = q.u1;
;         v[0] += bf_lo(pw.x); v[1] += bf_hi(pw.x); v[2] += bf_lo(pw.y); v[3] += bf_hi(pw.y); v[4] += bf_lo(pw.z); v[5] += bf_hi(pw.z); v[6] += bf_lo(pw.w); v[7] += bf_hi(pw.w); }
;       if (br == 2) store8bf((bf16_t*)e.out + (size_t)row * DM + col, v);
;       else store8bf(fa, v);
	v_lshlrev_b32_e32 v204, 16, v154
	v_and_b32_e32 v205, 0xffff0000, v154
	v_lshlrev_b32_e32 v206, 16, v158
	v_and_b32_e32 v207, 0xffff0000, v158
	v_pk_fma_f32 v[36:37], v[36:37], v[204:205], v[206:207]
	v_lshlrev_b32_e32 v204, 16, v155
	v_and_b32_e32 v205, 0xffff0000, v155
	v_lshlrev_b32_e32 v206, 16, v159
	v_and_b32_e32 v207, 0xffff0000, v159
	v_pk_fma_f32 v[38:39], v[38:39], v[204:205], v[206:207]
	v_lshlrev_b32_e32 v204, 16, v156
	v_and_b32_e32 v205, 0xffff0000, v156
	v_lshlrev_b32_e32 v206, 16, v160
	v_and_b32_e32 v207, 0xffff0000, v160
	v_pk_fma_f32 v[32:33], v[32:33], v[204:205], v[206:207]
	v_lshlrev_b32_e32 v204, 16, v157
	v_and_b32_e32 v205, 0xffff0000, v157
	v_lshlrev_b32_e32 v206, 16, v161
	v_and_b32_e32 v207, 0xffff0000, v161
	v_pk_fma_f32 v[34:35], v[34:35], v[204:205], v[206:207]
	v_cvt_pk_bf16_f32 v36, v36, v37
	v_cvt_pk_bf16_f32 v37, v38, v39
	v_cvt_pk_bf16_f32 v38, v32, v33
	v_cvt_pk_bf16_f32 v39, v34, v35
	global_store_dwordx4 v215, v[36:39], s[12:13] offset:256
	s_waitcnt vmcnt(18)
	v_lshlrev_b32_e32 v204, 16, v162
	v_and_b32_e32 v205, 0xffff0000, v162
	v_lshlrev_b32_e32 v206, 16, v166
	v_and_b32_e32 v207, 0xffff0000, v166
	v_pk_fma_f32 v[28:29], v[28:29], v[204:205], v[206:207]
	v_lshlrev_b32_e32 v204, 16, v163
	v_and_b32_e32 v205, 0xffff0000, v163
	v_lshlrev_b32_e32 v206, 16, v167
	v_and_b32_e32 v207, 0xffff0000, v167
	v_pk_fma_f32 v[30:31], v[30:31], v[204:205], v[206:207]
	v_lshlrev_b32_e32 v204, 16, v164
	v_and_b32_e32 v205, 0xffff0000, v164
	v_lshlrev_b32_e32 v206, 16, v168
	v_and_b32_e32 v207, 0xffff0000, v168
	v_pk_fma_f32 v[24:25], v[24:25], v[204:205], v[206:207]
	v_lshlrev_b32_e32 v204, 16, v165
	v_and_b32_e32 v205, 0xffff0000, v165
	v_lshlrev_b32_e32 v206, 16, v169
	v_and_b32_e32 v207, 0xffff0000, v169
	v_pk_fma_f32 v[26:27], v[26:27], v[204:205], v[206:207]
	v_cvt_pk_bf16_f32 v28, v28, v29
	v_cvt_pk_bf16_f32 v29, v30, v31
	v_cvt_pk_bf16_f32 v30, v24, v25
	v_cvt_pk_bf16_f32 v31, v26, v27
	v_add_u32_e32 v215, 0xa0000, v209
	global_store_dwordx4 v215, v[28:31], s[12:13]
	s_waitcnt vmcnt(17)
	v_lshlrev_b32_e32 v204, 16, v170
	v_and_b32_e32 v205, 0xffff0000, v170
	v_lshlrev_b32_e32 v206, 16, v174
	v_and_b32_e32 v207, 0xffff0000, v174
	v_pk_fma_f32 v[20:21], v[20:21], v[204:205], v[206:207]
	v_lshlrev_b32_e32 v204, 16, v171
	v_and_b32_e32 v205, 0xffff0000, v171
	v_lshlrev_b32_e32 v206, 16, v175
	v_and_b32_e32 v207, 0xffff0000, v175
	v_pk_fma_f32 v[22:23], v[22:23], v[204:205], v[206:207]
	v_lshlrev_b32_e32 v204, 16, v172
	v_and_b32_e32 v205, 0xffff0000, v172
	v_lshlrev_b32_e32 v206, 16, v176
	v_and_b32_e32 v207, 0xffff0000, v176
	v_pk_fma_f32 v[16:17], v[16:17], v[204:205], v[206:207]
	v_lshlrev_b32_e32 v204, 16, v173
	v_and_b32_e32 v205, 0xffff0000, v173
	v_lshlrev_b32_e32 v206, 16, v177
	v_and_b32_e32 v207, 0xffff0000, v177
	v_pk_fma_f32 v[18:19], v[18:19], v[204:205], v[206:207]
	v_cvt_pk_bf16_f32 v20, v20, v21
	v_cvt_pk_bf16_f32 v21, v22, v23
	v_cvt_pk_bf16_f32 v22, v16, v17
	v_cvt_pk_bf16_f32 v23, v18, v19
	global_store_dwordx4 v215, v[20:23], s[12:13] offset:256
	s_waitcnt vmcnt(16)
	v_lshlrev_b32_e32 v204, 16, v178
	v_and_b32_e32 v205, 0xffff0000, v178
	v_lshlrev_b32_e32 v206, 16, v182
	v_and_b32_e32 v207, 0xffff0000, v182
	v_pk_fma_f32 v[12:13], v[12:13], v[204:205], v[206:207]
	v_lshlrev_b32_e32 v204, 16, v179
	v_and_b32_e32 v205, 0xffff0000, v179
	v_lshlrev_b32_e32 v206, 16, v183
	v_and_b32_e32 v207, 0xffff0000, v183
	v_pk_fma_f32 v[14:15], v[14:15], v[204:205], v[206:207]
	v_lshlrev_b32_e32 v204, 16, v180
	v_and_b32_e32 v205, 0xffff0000, v180
	v_lshlrev_b32_e32 v206, 16, v184
	v_and_b32_e32 v207, 0xffff0000, v184
	v_pk_fma_f32 v[8:9], v[8:9], v[204:205], v[206:207]
	v_lshlrev_b32_e32 v204, 16, v181
	v_and_b32_e32 v205, 0xffff0000, v181
	v_lshlrev_b32_e32 v206, 16, v185
	v_and_b32_e32 v207, 0xffff0000, v185
	v_pk_fma_f32 v[10:11], v[10:11], v[204:205], v[206:207]
	v_cvt_pk_bf16_f32 v12, v12, v13
	v_cvt_pk_bf16_f32 v13, v14, v15
	v_cvt_pk_bf16_f32 v14, v8, v9
	v_cvt_pk_bf16_f32 v15, v10, v11
	v_add_u32_e32 v215, 0xb0000, v209
	global_store_dwordx4 v215, v[12:15], s[12:13]
	s_waitcnt vmcnt(15)
	v_lshlrev_b32_e32 v204, 16, v196
	v_and_b32_e32 v205, 0xffff0000, v196
	v_lshlrev_b32_e32 v206, 16, v200
	v_and_b32_e32 v207, 0xffff0000, v200
	v_pk_fma_f32 v[4:5], v[4:5], v[204:205], v[206:207]
	v_lshlrev_b32_e32 v204, 16, v197
	v_and_b32_e32 v205, 0xffff0000, v197
	v_lshlrev_b32_e32 v206, 16, v201
	v_and_b32_e32 v207, 0xffff0000, v201
	v_pk_fma_f32 v[6:7], v[6:7], v[204:205], v[206:207]
	v_lshlrev_b32_e32 v204, 16, v198
	v_and_b32_e32 v205, 0xffff0000, v198
	v_lshlrev_b32_e32 v206, 16, v202
	v_and_b32_e32 v207, 0xffff0000, v202
	v_pk_fma_f32 v[0:1], v[0:1], v[204:205], v[206:207]
	v_lshlrev_b32_e32 v204, 16, v199
	v_and_b32_e32 v205, 0xffff0000, v199
	v_lshlrev_b32_e32 v206, 16, v203
	v_and_b32_e32 v207, 0xffff0000, v203
	v_pk_fma_f32 v[2:3], v[2:3], v[204:205], v[206:207]
	v_cvt_pk_bf16_f32 v4, v4, v5
	v_cvt_pk_bf16_f32 v5, v6, v7
	v_cvt_pk_bf16_f32 v6, v0, v1
	v_cvt_pk_bf16_f32 v7, v2, v3
	global_store_dwordx4 v215, v[4:7], s[12:13] offset:256
	s_mov_b32 s47, s14
	s_mov_b64 s[22:23], s[18:19]
	s_mov_b64 s[20:21], s[16:17]
	s_and_b64 vcc, exec, s[2:3]
	s_mov_b32 s1, s46
	s_cbranch_vccz .LBB0_1016
	s_waitcnt vmcnt(0)
	s_cmpk_gt_u32 s29, 0xff
	s_cbranch_scc1 .LBB0_1029
	s_barrier
